# v11 + gate/up epilogue row-ssq loads issued at top of last K iteration, counted vmcnt(16) instead of vmcnt(0)
# baseline (speedup 1.0000x reference)
; __device__ __forceinline__ float siluf_(float x) { return x * sigmoidf_(x); }
; __device__ __forceinline__ float rinv_of(float ssq) { return rsqrtf(ssq * (1.0f / 1024.0f) + EPS); }
; __device__ __forceinline__ u32x4 pack8(const f32x4 a, const f32x4 b) { u32x4 w; w.x = cvt_pk_bf16(a[0], a[1]); w.y = cvt_pk_bf16(a[2], a[3]); w.z = cvt_pk_bf16(b[0], b[1]); w.w = cvt_pk_bf16(b[2], b[3]); return w; }
;     __device__ __forceinline__ void operator()(const AccT& acc, const pg8::Unit& u, int wr, int wc, int fr, int fq) const {
;         asm volatile("" : "+v"(fr), "+v"(fq), "+s"(wr), "+s"(wc));
;         float ris[2][4];
; #pragma unroll
;         for (int ai = 0; ai < 2; ++ai)
; #pragma unroll
;             for (int m = 0; m < 4; ++m) ris[ai][m] = ssq_in[EPI_ROW(u, ai, m)];
; #pragma unroll
;         for (int ai = 0; ai < 2; ++ai)
; #pragma unroll
;             for (int m = 0; m < 4; ++m) {
;                 const int r = EPI_ROW(u, ai, m); const float ri = rinv_of(ris[ai][m]);
;                 f32x4 o[2];
; #pragma unroll
;                 for (int n = 0; n < 2; ++n) { const f32x4 gt = acc[ai][0][m][n] * ri, up = acc[ai][1][m][n] * ri;
; #pragma unroll
;                     for (int j = 0; j < 4; ++j) o[n][j] = siluf_(gt[j]) * up[j]; }
;                 *(u32x4*)(act + (size_t)r * DFF + u.pn * 128 + wc * 32 + 8 * fq) = pack8(o[0], o[1]); }
.LBB0_1535:
	s_mov_b32 s15, s42
	v_mov_b32_e32 v144, v148
	s_mov_b32 s8, s35
	v_mov_b32_e32 v155, v149
	s_lshl_b32 s9, s24, 8
	s_lshl_b32 s8, s8, 6
	s_add_i32 s8, s8, s9
	v_add_u32_e32 v156, s8, v144
	v_ashrrev_i32_e32 v157, 31, v156
	v_lshl_add_u64 v[144:145], v[156:157], 2, s[20:21]
	v_add_u32_e32 v166, 16, v156
	v_mov_b32_e32 v158, v124
	v_mov_b32_e32 v160, v126
	v_mov_b32_e32 v162, v120
	v_mov_b32_e32 v164, v122
	v_add_u32_e32 v146, 32, v156
	v_add_u32_e32 v144, 48, v156
	v_add_u32_e32 v126, 0x80, v156
	v_add_u32_e32 v124, 0x90, v156
	v_add_u32_e32 v122, 0xa0, v156
	v_add_u32_e32 v120, 0xb0, v156
	v_ashrrev_i32_e32 v167, 31, v166
	v_mov_b32_e32 v159, v116
	v_mov_b32_e32 v116, v125
	v_mov_b32_e32 v161, v118
	v_mov_b32_e32 v118, v127
	v_mov_b32_e32 v163, v112
	v_mov_b32_e32 v112, v121
	v_mov_b32_e32 v165, v114
	v_mov_b32_e32 v114, v123
	v_ashrrev_i32_e32 v147, 31, v146
	v_ashrrev_i32_e32 v145, 31, v144
	v_ashrrev_i32_e32 v127, 31, v126
	v_ashrrev_i32_e32 v125, 31, v124
	v_ashrrev_i32_e32 v123, 31, v122
	v_ashrrev_i32_e32 v121, 31, v120
	v_lshl_add_u64 v[168:169], v[166:167], 2, s[20:21]
	v_lshl_add_u64 v[170:171], v[146:147], 2, s[20:21]
	v_lshl_add_u64 v[172:173], v[144:145], 2, s[20:21]
	v_lshl_add_u64 v[174:175], v[126:127], 2, s[20:21]
	v_lshl_add_u64 v[176:177], v[124:125], 2, s[20:21]
	v_lshl_add_u64 v[178:179], v[122:123], 2, s[20:21]
	v_lshl_add_u64 v[180:181], v[120:121], 2, s[20:21]
	s_lshl_b32 s8, s25, 7
	s_ashr_i32 s9, s8, 31
	s_lshl_b32 s24, s15, 5
	s_ashr_i32 s25, s24, 31
	s_lshl_b64 s[8:9], s[8:9], 1
	s_lshl_b64 s[24:25], s[24:25], 1
	s_mov_b64 s[28:29], s[18:19]
	s_waitcnt vmcnt(16)
	v_mov_b32_e32 v157, v248
	v_mov_b32_e32 v127, v249
	v_mov_b32_e32 v145, v250
	v_mov_b32_e32 v147, v251
	v_mov_b32_e32 v167, v252
	v_mov_b32_e32 v125, v253
	v_mov_b32_e32 v123, v254
	v_mov_b32_e32 v121, v255
	v_fmamk_f32 v157, v157, 0x3a800000, v154
	v_mul_f32_e32 v168, 0x4b800000, v157
	v_cmp_gt_f32_e32 vcc, s61, v157
	v_fmamk_f32 v127, v127, 0x3a800000, v154
	s_nop 0
	v_cndmask_b32_e32 v157, v157, v168, vcc
	v_rsq_f32_e32 v157, v157
	v_lshlrev_b32_e32 v168, 3, v155
	v_ashrrev_i32_e32 v169, 31, v168
	v_mul_f32_e32 v155, 0x45800000, v157
	v_cndmask_b32_e32 v170, v157, v155, vcc
	v_pk_mul_f32 v[158:159], v[158:159], v[170:171] op_sel_hi:[1,0]
	v_pk_mul_f32 v[116:117], v[116:117], v[170:171] op_sel_hi:[1,0]
	v_mul_f32_e32 v155, 0xbfb8aa3b, v159
	v_mul_f32_e32 v157, 0xbfb8aa3b, v117
	v_exp_f32_e32 v155, v155
	v_exp_f32_e32 v157, v157
	v_pk_mul_f32 v[160:161], v[160:161], v[170:171] op_sel_hi:[1,0]
	v_pk_mul_f32 v[118:119], v[118:119], v[170:171] op_sel_hi:[1,0]
	v_pk_mul_f32 v[162:163], v[162:163], v[170:171] op_sel_hi:[1,0]
	v_pk_mul_f32 v[112:113], v[112:113], v[170:171] op_sel_hi:[1,0]
	v_pk_mul_f32 v[164:165], v[164:165], v[170:171] op_sel_hi:[1,0]
	v_pk_mul_f32 v[114:115], v[114:115], v[170:171] op_sel_hi:[1,0]
	v_mul_f32_e32 v170, 0xbfb8aa3b, v161
	v_exp_f32_e32 v170, v170
	v_add_f32_e32 v155, 1.0, v155
	v_add_f32_e32 v157, 1.0, v157
	v_rcp_f32_e32 v155, v155
	v_rcp_f32_e32 v157, v157
	v_mul_f32_e32 v173, 0xbfb8aa3b, v113
	v_mul_f32_e32 v172, 0xbfb8aa3b, v163
	v_mul_f32_e32 v174, 0xbfb8aa3b, v165
	v_exp_f32_e32 v173, v173
	v_add_f32_e32 v170, 1.0, v170
	v_exp_f32_e32 v172, v172
	v_exp_f32_e32 v174, v174
	v_rcp_f32_e32 v170, v170
	v_mul_f32_e32 v155, v159, v155
	v_mul_f32_e32 v117, v117, v157
	v_mul_f32_e32 v155, v158, v155
	v_mul_f32_e32 v116, v116, v117
	v_cvt_pk_bf16_f32 v116, v155, v116
	v_mul_f32_e32 v155, 0x4b800000, v127
	v_cmp_gt_f32_e32 vcc, s61, v127
	v_add_f32_e32 v173, 1.0, v173
	v_mul_f32_e32 v171, 0xbfb8aa3b, v119
	v_cndmask_b32_e32 v127, v127, v155, vcc
	v_add_f32_e32 v172, 1.0, v172
	v_rcp_f32_e32 v173, v173
	v_mul_f32_e32 v157, v161, v170
	v_add_f32_e32 v158, 1.0, v174
	v_rsq_f32_e32 v127, v127
	v_exp_f32_e32 v171, v171
	v_rcp_f32_e32 v172, v172
	v_mul_f32_e32 v117, v160, v157
	v_mul_f32_e32 v157, 0xbfb8aa3b, v115
	v_rcp_f32_e32 v158, v158
	v_exp_f32_e32 v157, v157
	v_mul_f32_e32 v113, v113, v173
	v_mul_f32_e32 v155, 0x45800000, v127
	v_add_f32_e32 v171, 1.0, v171
	v_mul_f32_e32 v159, v163, v172
	v_mul_f32_e32 v112, v112, v113
	v_mul_f32_e32 v113, v165, v158
	v_cndmask_b32_e32 v158, v127, v155, vcc
	v_mov_b32_e32 v160, v108
	v_mov_b32_e32 v161, v104
	v_rcp_f32_e32 v171, v171
	v_add_f32_e32 v157, 1.0, v157
	v_pk_mul_f32 v[160:161], v[160:161], v[158:159] op_sel_hi:[1,0]
	v_rcp_f32_e32 v157, v157
	v_mul_f32_e32 v104, 0xbfb8aa3b, v161
	v_exp_f32_e32 v127, v104
	v_mul_f32_e32 v119, v119, v171
	v_mul_f32_e32 v118, v118, v119
	v_mul_f32_e32 v119, v162, v159
	v_mul_f32_e32 v113, v164, v113
	v_mul_f32_e32 v115, v115, v157
	v_mul_f32_e32 v114, v114, v115
	v_cvt_pk_bf16_f32 v117, v117, v118
	v_cvt_pk_bf16_f32 v118, v119, v112
	v_cvt_pk_bf16_f32 v119, v113, v114
	v_mov_b64_e32 v[112:113], s[74:75]
	v_add_f32_e32 v127, 1.0, v127
	v_mad_i64_i32 v[114:115], s[26:27], v156, s62, v[112:113]
	v_mov_b32_e32 v104, v109
	v_rcp_f32_e32 v127, v127
	v_lshl_add_u64 v[114:115], v[114:115], 0, s[8:9]
	v_pk_mul_f32 v[104:105], v[104:105], v[158:159] op_sel_hi:[1,0]
	v_lshl_add_u64 v[156:157], v[114:115], 0, s[24:25]
	v_lshlrev_b64 v[114:115], 1, v[168:169]
	v_mul_f32_e32 v108, 0xbfb8aa3b, v105
	v_exp_f32_e32 v155, v108
	v_lshl_add_u64 v[108:109], v[156:157], 0, v[114:115]
	global_store_dwordx4 v[108:109], v[116:119], off
	v_mul_f32_e32 v108, v161, v127
	v_mov_b32_e32 v109, v106
	v_mul_f32_e32 v116, v160, v108
	v_mov_b32_e32 v108, v110
	v_pk_mul_f32 v[108:109], v[108:109], v[158:159] op_sel_hi:[1,0]
	v_add_f32_e32 v155, 1.0, v155
	v_mul_f32_e32 v106, 0xbfb8aa3b, v109
	v_exp_f32_e32 v110, v106
	v_mov_b32_e32 v106, v111
	v_rcp_f32_e32 v155, v155
; __device__ __forceinline__ float siluf_(float x) { return x * sigmoidf_(x); }
; __device__ __forceinline__ float rinv_of(float ssq) { return rsqrtf(ssq * (1.0f / 1024.0f) + EPS); }
; __device__ __forceinline__ u32x4 pack8(const f32x4 a, const f32x4 b) { u32x4 w; w.x = cvt_pk_bf16(a[0], a[1]); w.y = cvt_pk_bf16(a[2], a[3]); w.z = cvt_pk_bf16(b[0], b[1]); w.w = cvt_pk_bf16(b[2], b[3]); return w; }
;     __device__ __forceinline__ void operator()(const AccT& acc, const pg8::Unit& u, int wr, int wc, int fr, int fq) const {
;     ...
;             for (int m = 0; m < 4; ++m) {
;                 const int r = EPI_ROW(u, ai, m); const float ri = rinv_of(ris[ai][m]);
;                 f32x4 o[2];
; #pragma unroll
;                 for (int n = 0; n < 2; ++n) { const f32x4 gt = acc[ai][0][m][n] * ri, up = acc[ai][1][m][n] * ri;
; #pragma unroll
;                     for (int j = 0; j < 4; ++j) o[n][j] = siluf_(gt[j]) * up[j]; }
;                 *(u32x4*)(act + (size_t)r * DFF + u.pn * 128 + wc * 32 + 8 * fq) = pack8(o[0], o[1]); }
	v_pk_mul_f32 v[106:107], v[106:107], v[158:159] op_sel_hi:[1,0]
	v_mul_f32_e32 v105, v105, v155
	v_mul_f32_e32 v111, 0xbfb8aa3b, v107
	v_exp_f32_e32 v111, v111
	v_mul_f32_e32 v117, v104, v105
	v_add_f32_e32 v104, 1.0, v110
	v_rcp_f32_e32 v110, v104
	v_add_f32_e32 v104, 1.0, v111
	v_rcp_f32_e32 v111, v104
	v_mov_b32_e32 v104, v100
	v_mov_b32_e32 v105, v96
	v_pk_mul_f32 v[104:105], v[104:105], v[158:159] op_sel_hi:[1,0]
	v_mul_f32_e32 v100, v109, v110
	v_mul_f32_e32 v96, 0xbfb8aa3b, v105
	v_exp_f32_e32 v96, v96
	v_mul_f32_e32 v108, v108, v100
	v_mul_f32_e32 v100, v107, v111
	v_mul_f32_e32 v106, v106, v100
	v_add_f32_e32 v96, 1.0, v96
	v_rcp_f32_e32 v107, v96
	v_mov_b32_e32 v96, v101
	v_pk_mul_f32 v[96:97], v[96:97], v[158:159] op_sel_hi:[1,0]
	v_mul_f32_e32 v100, v105, v107
	v_mul_f32_e32 v101, 0xbfb8aa3b, v97
	v_exp_f32_e32 v101, v101
	v_mul_f32_e32 v104, v104, v100
	v_add_f32_e32 v100, 1.0, v101
	v_rcp_f32_e32 v105, v100
	v_mov_b32_e32 v100, v102
	v_mov_b32_e32 v101, v98
	v_pk_mul_f32 v[100:101], v[100:101], v[158:159] op_sel_hi:[1,0]
	v_mul_f32_e32 v97, v97, v105
	v_mul_f32_e32 v98, 0xbfb8aa3b, v101
	v_exp_f32_e32 v102, v98
	v_mov_b32_e32 v98, v103
	v_pk_mul_f32 v[98:99], v[98:99], v[158:159] op_sel_hi:[1,0]
	v_mul_f32_e32 v105, v96, v97
	v_mul_f32_e32 v103, 0xbfb8aa3b, v99
	v_exp_f32_e32 v103, v103
	v_add_f32_e32 v102, 1.0, v102
	v_rcp_f32_e32 v102, v102
	v_add_f32_e32 v103, 1.0, v103
	v_rcp_f32_e32 v103, v103
	v_mul_f32_e32 v96, v101, v102
	v_mul_f32_e32 v100, v100, v96
	v_mul_f32_e32 v96, v99, v103
	v_mul_f32_e32 v99, v98, v96
	v_cvt_pk_bf16_f32 v96, v116, v117
	v_cvt_pk_bf16_f32 v97, v108, v106
	v_cvt_pk_bf16_f32 v98, v104, v105
	v_cvt_pk_bf16_f32 v99, v100, v99
	v_fmamk_f32 v100, v145, 0x3a800000, v154
	v_mul_f32_e32 v101, 0x4b800000, v100
	v_cmp_gt_f32_e32 vcc, s61, v100
	v_mov_b32_e32 v104, v92
	v_mov_b32_e32 v105, v88
	v_cndmask_b32_e32 v100, v100, v101, vcc
	v_rsq_f32_e32 v102, v100
	v_mad_i64_i32 v[100:101], s[26:27], v166, s62, v[112:113]
	v_lshl_add_u64 v[100:101], v[100:101], 0, s[8:9]
	v_mul_f32_e32 v103, 0x45800000, v102
	v_cndmask_b32_e32 v102, v102, v103, vcc
	v_pk_mul_f32 v[104:105], v[104:105], v[102:103] op_sel_hi:[1,0]
	v_lshl_add_u64 v[100:101], v[100:101], 0, s[24:25]
	v_mul_f32_e32 v88, 0xbfb8aa3b, v105
	v_exp_f32_e32 v103, v88
	v_mov_b32_e32 v88, v93
	v_pk_mul_f32 v[88:89], v[88:89], v[102:103] op_sel_hi:[1,0]
	s_nop 0
	v_mul_f32_e32 v92, 0xbfb8aa3b, v89
	v_exp_f32_e32 v106, v92
	v_lshl_add_u64 v[92:93], v[100:101], 0, v[114:115]
	v_add_f32_e32 v100, 1.0, v103
	v_rcp_f32_e32 v100, v100
	global_store_dwordx4 v[92:93], v[96:99], off
	v_mov_b32_e32 v93, v90
	v_add_f32_e32 v101, 1.0, v106
	v_mul_f32_e32 v92, v105, v100
	v_mul_f32_e32 v96, v104, v92
	v_mov_b32_e32 v92, v94
	v_pk_mul_f32 v[92:93], v[92:93], v[102:103] op_sel_hi:[1,0]
	v_rcp_f32_e32 v101, v101
	v_mul_f32_e32 v90, 0xbfb8aa3b, v93
	v_exp_f32_e32 v94, v90
	v_mov_b32_e32 v90, v95
	v_pk_mul_f32 v[90:91], v[90:91], v[102:103] op_sel_hi:[1,0]
	v_mul_f32_e32 v89, v89, v101
	v_mul_f32_e32 v95, 0xbfb8aa3b, v91
	v_exp_f32_e32 v95, v95
	v_mul_f32_e32 v97, v88, v89
	v_add_f32_e32 v88, 1.0, v94
	v_rcp_f32_e32 v94, v88
	v_add_f32_e32 v88, 1.0, v95
	v_rcp_f32_e32 v95, v88
	v_mov_b32_e32 v88, v84
	v_mov_b32_e32 v89, v80
	v_pk_mul_f32 v[88:89], v[88:89], v[102:103] op_sel_hi:[1,0]
	v_mul_f32_e32 v84, v93, v94
	v_mul_f32_e32 v80, 0xbfb8aa3b, v89
	v_exp_f32_e32 v80, v80
	v_mul_f32_e32 v92, v92, v84
	v_mul_f32_e32 v84, v91, v95
	v_mul_f32_e32 v90, v90, v84
	v_add_f32_e32 v80, 1.0, v80
	v_rcp_f32_e32 v91, v80
	v_mov_b32_e32 v80, v85
	v_pk_mul_f32 v[80:81], v[80:81], v[102:103] op_sel_hi:[1,0]
	v_mul_f32_e32 v84, v89, v91
	v_mul_f32_e32 v85, 0xbfb8aa3b, v81
	v_exp_f32_e32 v85, v85
	v_mul_f32_e32 v88, v88, v84
	v_add_f32_e32 v84, 1.0, v85
	v_rcp_f32_e32 v89, v84
	v_mov_b32_e32 v84, v86
	v_mov_b32_e32 v85, v82
	v_pk_mul_f32 v[84:85], v[84:85], v[102:103] op_sel_hi:[1,0]
	v_mul_f32_e32 v81, v81, v89
	v_mul_f32_e32 v82, 0xbfb8aa3b, v85
	v_exp_f32_e32 v86, v82
	v_mov_b32_e32 v82, v87
	v_pk_mul_f32 v[82:83], v[82:83], v[102:103] op_sel_hi:[1,0]
	v_mul_f32_e32 v89, v80, v81
	v_mul_f32_e32 v87, 0xbfb8aa3b, v83
	v_exp_f32_e32 v87, v87
	v_add_f32_e32 v86, 1.0, v86
	v_rcp_f32_e32 v86, v86
	v_add_f32_e32 v87, 1.0, v87
	v_rcp_f32_e32 v87, v87
	v_mul_f32_e32 v80, v85, v86
	v_mul_f32_e32 v84, v84, v80
	v_mul_f32_e32 v80, v83, v87
	v_mul_f32_e32 v83, v82, v80
	v_cvt_pk_bf16_f32 v80, v96, v97
	v_cvt_pk_bf16_f32 v81, v92, v90
	v_cvt_pk_bf16_f32 v82, v88, v89
	v_cvt_pk_bf16_f32 v83, v84, v83
	v_fmamk_f32 v84, v147, 0x3a800000, v154
	v_mul_f32_e32 v85, 0x4b800000, v84
	v_cmp_gt_f32_e32 vcc, s61, v84
	v_mov_b32_e32 v88, v76
	v_mov_b32_e32 v89, v72
	v_cndmask_b32_e32 v84, v84, v85, vcc
	v_rsq_f32_e32 v86, v84
	v_mad_i64_i32 v[84:85], s[26:27], v146, s62, v[112:113]
	v_lshl_add_u64 v[84:85], v[84:85], 0, s[8:9]
	v_mul_f32_e32 v87, 0x45800000, v86
	v_cndmask_b32_e32 v86, v86, v87, vcc
	v_pk_mul_f32 v[88:89], v[88:89], v[86:87] op_sel_hi:[1,0]
	v_lshl_add_u64 v[84:85], v[84:85], 0, s[24:25]
	v_mul_f32_e32 v72, 0xbfb8aa3b, v89
	v_exp_f32_e32 v87, v72
	v_mov_b32_e32 v72, v77
	v_pk_mul_f32 v[72:73], v[72:73], v[86:87] op_sel_hi:[1,0]
	s_nop 0
	v_mul_f32_e32 v76, 0xbfb8aa3b, v73
	v_exp_f32_e32 v90, v76
	v_lshl_add_u64 v[76:77], v[84:85], 0, v[114:115]
	v_add_f32_e32 v84, 1.0, v87
	v_rcp_f32_e32 v84, v84
	global_store_dwordx4 v[76:77], v[80:83], off
	v_mov_b32_e32 v77, v74
	v_add_f32_e32 v85, 1.0, v90
	v_mul_f32_e32 v76, v89, v84
	v_mul_f32_e32 v80, v88, v76
	v_mov_b32_e32 v76, v78
	v_pk_mul_f32 v[76:77], v[76:77], v[86:87] op_sel_hi:[1,0]
	v_rcp_f32_e32 v85, v85
	v_mul_f32_e32 v74, 0xbfb8aa3b, v77
; __device__ __forceinline__ float siluf_(float x) { return x * sigmoidf_(x); }
; __device__ __forceinline__ float rinv_of(float ssq) { return rsqrtf(ssq * (1.0f / 1024.0f) + EPS); }
; __device__ __forceinline__ u32x4 pack8(const f32x4 a, const f32x4 b) { u32x4 w; w.x = cvt_pk_bf16(a[0], a[1]); w.y = cvt_pk_bf16(a[2], a[3]); w.z = cvt_pk_bf16(b[0], b[1]); w.w = cvt_pk_bf16(b[2], b[3]); return w; }
;     __device__ __forceinline__ void operator()(const AccT& acc, const pg8::Unit& u, int wr, int wc, int fr, int fq) const {
;     ...
;             for (int m = 0; m < 4; ++m) {
;                 const int r = EPI_ROW(u, ai, m); const float ri = rinv_of(ris[ai][m]);
;                 f32x4 o[2];
; #pragma unroll
;                 for (int n = 0; n < 2; ++n) { const f32x4 gt = acc[ai][0][m][n] * ri, up = acc[ai][1][m][n] * ri;
; #pragma unroll
;                     for (int j = 0; j < 4; ++j) o[n][j] = siluf_(gt[j]) * up[j]; }
;                 *(u32x4*)(act + (size_t)r * DFF + u.pn * 128 + wc * 32 + 8 * fq) = pack8(o[0], o[1]); }
	v_exp_f32_e32 v78, v74
	v_mov_b32_e32 v74, v79
	v_pk_mul_f32 v[74:75], v[74:75], v[86:87] op_sel_hi:[1,0]
	v_mul_f32_e32 v73, v73, v85
	v_mul_f32_e32 v79, 0xbfb8aa3b, v75
	v_exp_f32_e32 v79, v79
	v_mul_f32_e32 v81, v72, v73
	v_add_f32_e32 v72, 1.0, v78
	v_rcp_f32_e32 v78, v72
	v_add_f32_e32 v72, 1.0, v79
	v_rcp_f32_e32 v79, v72
	v_mov_b32_e32 v72, v68
	v_mov_b32_e32 v73, v64
	v_pk_mul_f32 v[72:73], v[72:73], v[86:87] op_sel_hi:[1,0]
	v_mul_f32_e32 v68, v77, v78
	v_mul_f32_e32 v64, 0xbfb8aa3b, v73
	v_exp_f32_e32 v64, v64
	v_mul_f32_e32 v76, v76, v68
	v_mul_f32_e32 v68, v75, v79
	v_mul_f32_e32 v74, v74, v68
	v_add_f32_e32 v64, 1.0, v64
	v_rcp_f32_e32 v75, v64
	v_mov_b32_e32 v64, v69
	v_pk_mul_f32 v[64:65], v[64:65], v[86:87] op_sel_hi:[1,0]
	v_mul_f32_e32 v68, v73, v75
	v_mul_f32_e32 v69, 0xbfb8aa3b, v65
	v_exp_f32_e32 v69, v69
	v_mul_f32_e32 v72, v72, v68
	v_add_f32_e32 v68, 1.0, v69
	v_rcp_f32_e32 v73, v68
	v_mov_b32_e32 v68, v70
	v_mov_b32_e32 v69, v66
	v_pk_mul_f32 v[68:69], v[68:69], v[86:87] op_sel_hi:[1,0]
	v_mul_f32_e32 v65, v65, v73
	v_mul_f32_e32 v66, 0xbfb8aa3b, v69
	v_exp_f32_e32 v70, v66
	v_mov_b32_e32 v66, v71
	v_pk_mul_f32 v[66:67], v[66:67], v[86:87] op_sel_hi:[1,0]
	v_mul_f32_e32 v73, v64, v65
	v_mul_f32_e32 v71, 0xbfb8aa3b, v67
	v_exp_f32_e32 v71, v71
	v_add_f32_e32 v70, 1.0, v70
	v_rcp_f32_e32 v70, v70
	v_add_f32_e32 v71, 1.0, v71
	v_rcp_f32_e32 v71, v71
	v_mul_f32_e32 v64, v69, v70
	v_mul_f32_e32 v68, v68, v64
	v_mul_f32_e32 v64, v67, v71
	v_mul_f32_e32 v67, v66, v64
	v_cvt_pk_bf16_f32 v64, v80, v81
	v_cvt_pk_bf16_f32 v65, v76, v74
	v_cvt_pk_bf16_f32 v66, v72, v73
	v_cvt_pk_bf16_f32 v67, v68, v67
	v_fmamk_f32 v68, v167, 0x3a800000, v154
	v_mul_f32_e32 v69, 0x4b800000, v68
	v_cmp_gt_f32_e32 vcc, s61, v68
	v_mov_b32_e32 v72, v60
	v_mov_b32_e32 v73, v56
	v_cndmask_b32_e32 v68, v68, v69, vcc
	v_rsq_f32_e32 v70, v68
	v_mad_i64_i32 v[68:69], s[26:27], v144, s62, v[112:113]
	v_lshl_add_u64 v[68:69], v[68:69], 0, s[8:9]
	v_mul_f32_e32 v71, 0x45800000, v70
	v_cndmask_b32_e32 v70, v70, v71, vcc
	v_pk_mul_f32 v[72:73], v[72:73], v[70:71] op_sel_hi:[1,0]
	v_lshl_add_u64 v[68:69], v[68:69], 0, s[24:25]
	v_mul_f32_e32 v56, 0xbfb8aa3b, v73
	v_exp_f32_e32 v71, v56
	v_mov_b32_e32 v56, v61
	v_pk_mul_f32 v[56:57], v[56:57], v[70:71] op_sel_hi:[1,0]
	s_nop 0
	v_mul_f32_e32 v60, 0xbfb8aa3b, v57
	v_exp_f32_e32 v74, v60
	v_lshl_add_u64 v[60:61], v[68:69], 0, v[114:115]
	v_add_f32_e32 v68, 1.0, v71
	v_rcp_f32_e32 v68, v68
	global_store_dwordx4 v[60:61], v[64:67], off
	v_mov_b32_e32 v61, v58
	v_add_f32_e32 v69, 1.0, v74
	v_mul_f32_e32 v60, v73, v68
	v_mul_f32_e32 v64, v72, v60
	v_mov_b32_e32 v60, v62
	v_pk_mul_f32 v[60:61], v[60:61], v[70:71] op_sel_hi:[1,0]
	v_rcp_f32_e32 v69, v69
	v_mul_f32_e32 v58, 0xbfb8aa3b, v61
	v_exp_f32_e32 v62, v58
	v_mov_b32_e32 v58, v63
	v_pk_mul_f32 v[58:59], v[58:59], v[70:71] op_sel_hi:[1,0]
	v_mul_f32_e32 v57, v57, v69
	v_mul_f32_e32 v63, 0xbfb8aa3b, v59
	v_exp_f32_e32 v63, v63
	v_mul_f32_e32 v65, v56, v57
	v_add_f32_e32 v56, 1.0, v62
	v_rcp_f32_e32 v62, v56
	v_add_f32_e32 v56, 1.0, v63
	v_rcp_f32_e32 v63, v56
	v_mov_b32_e32 v56, v52
	v_mov_b32_e32 v57, v48
	v_pk_mul_f32 v[56:57], v[56:57], v[70:71] op_sel_hi:[1,0]
	v_mul_f32_e32 v52, v61, v62
	v_mul_f32_e32 v48, 0xbfb8aa3b, v57
	v_exp_f32_e32 v48, v48
	v_mul_f32_e32 v60, v60, v52
	v_mul_f32_e32 v52, v59, v63
	v_mul_f32_e32 v58, v58, v52
	v_add_f32_e32 v48, 1.0, v48
	v_rcp_f32_e32 v59, v48
	v_mov_b32_e32 v48, v53
	v_pk_mul_f32 v[48:49], v[48:49], v[70:71] op_sel_hi:[1,0]
	v_mul_f32_e32 v52, v57, v59
	v_mul_f32_e32 v53, 0xbfb8aa3b, v49
	v_exp_f32_e32 v53, v53
	v_mul_f32_e32 v56, v56, v52
	v_add_f32_e32 v52, 1.0, v53
	v_rcp_f32_e32 v57, v52
	v_mov_b32_e32 v52, v54
	v_mov_b32_e32 v53, v50
	v_pk_mul_f32 v[52:53], v[52:53], v[70:71] op_sel_hi:[1,0]
	v_mul_f32_e32 v49, v49, v57
	v_mul_f32_e32 v50, 0xbfb8aa3b, v53
	v_exp_f32_e32 v54, v50
	v_mov_b32_e32 v50, v55
	v_pk_mul_f32 v[50:51], v[50:51], v[70:71] op_sel_hi:[1,0]
	v_mul_f32_e32 v57, v48, v49
	v_mul_f32_e32 v55, 0xbfb8aa3b, v51
	v_exp_f32_e32 v55, v55
	v_add_f32_e32 v54, 1.0, v54
	v_rcp_f32_e32 v54, v54
	v_add_f32_e32 v55, 1.0, v55
	v_rcp_f32_e32 v55, v55
	v_mul_f32_e32 v48, v53, v54
	v_mul_f32_e32 v52, v52, v48
	v_mul_f32_e32 v48, v51, v55
	v_mul_f32_e32 v51, v50, v48
	v_cvt_pk_bf16_f32 v48, v64, v65
	v_cvt_pk_bf16_f32 v49, v60, v58
	v_cvt_pk_bf16_f32 v50, v56, v57
	v_cvt_pk_bf16_f32 v51, v52, v51
	v_fmamk_f32 v52, v125, 0x3a800000, v154
	v_mul_f32_e32 v53, 0x4b800000, v52
	v_cmp_gt_f32_e32 vcc, s61, v52
	v_mov_b32_e32 v56, v44
	v_mov_b32_e32 v57, v40
	v_cndmask_b32_e32 v52, v52, v53, vcc
	v_rsq_f32_e32 v54, v52
	v_mad_i64_i32 v[52:53], s[26:27], v126, s62, v[112:113]
	v_lshl_add_u64 v[52:53], v[52:53], 0, s[8:9]
	v_mul_f32_e32 v55, 0x45800000, v54
	v_cndmask_b32_e32 v54, v54, v55, vcc
	v_pk_mul_f32 v[56:57], v[56:57], v[54:55] op_sel_hi:[1,0]
	v_lshl_add_u64 v[52:53], v[52:53], 0, s[24:25]
	v_mul_f32_e32 v40, 0xbfb8aa3b, v57
	v_exp_f32_e32 v55, v40
	v_mov_b32_e32 v40, v45
	v_pk_mul_f32 v[40:41], v[40:41], v[54:55] op_sel_hi:[1,0]
	s_nop 0
	v_mul_f32_e32 v44, 0xbfb8aa3b, v41
	v_exp_f32_e32 v58, v44
	v_lshl_add_u64 v[44:45], v[52:53], 0, v[114:115]
	v_add_f32_e32 v52, 1.0, v55
	v_rcp_f32_e32 v52, v52
	global_store_dwordx4 v[44:45], v[48:51], off
	v_mov_b32_e32 v45, v42
	v_add_f32_e32 v53, 1.0, v58
	v_mul_f32_e32 v44, v57, v52
	v_mul_f32_e32 v48, v56, v44
	v_mov_b32_e32 v44, v46
	v_pk_mul_f32 v[44:45], v[44:45], v[54:55] op_sel_hi:[1,0]
	v_rcp_f32_e32 v53, v53
	v_mul_f32_e32 v42, 0xbfb8aa3b, v45
	v_exp_f32_e32 v46, v42
	v_mov_b32_e32 v42, v47
	v_pk_mul_f32 v[42:43], v[42:43], v[54:55] op_sel_hi:[1,0]
; __device__ __forceinline__ float siluf_(float x) { return x * sigmoidf_(x); }
; __device__ __forceinline__ float rinv_of(float ssq) { return rsqrtf(ssq * (1.0f / 1024.0f) + EPS); }
; __device__ __forceinline__ u32x4 pack8(const f32x4 a, const f32x4 b) { u32x4 w; w.x = cvt_pk_bf16(a[0], a[1]); w.y = cvt_pk_bf16(a[2], a[3]); w.z = cvt_pk_bf16(b[0], b[1]); w.w = cvt_pk_bf16(b[2], b[3]); return w; }
;     __device__ __forceinline__ void operator()(const AccT& acc, const pg8::Unit& u, int wr, int wc, int fr, int fq) const {
;     ...
;             for (int m = 0; m < 4; ++m) {
;                 const int r = EPI_ROW(u, ai, m); const float ri = rinv_of(ris[ai][m]);
;                 f32x4 o[2];
; #pragma unroll
;                 for (int n = 0; n < 2; ++n) { const f32x4 gt = acc[ai][0][m][n] * ri, up = acc[ai][1][m][n] * ri;
; #pragma unroll
;                     for (int j = 0; j < 4; ++j) o[n][j] = siluf_(gt[j]) * up[j]; }
;                 *(u32x4*)(act + (size_t)r * DFF + u.pn * 128 + wc * 32 + 8 * fq) = pack8(o[0], o[1]); }
	v_mul_f32_e32 v41, v41, v53
	v_mul_f32_e32 v47, 0xbfb8aa3b, v43
	v_exp_f32_e32 v47, v47
	v_mul_f32_e32 v49, v40, v41
	v_add_f32_e32 v40, 1.0, v46
	v_rcp_f32_e32 v46, v40
	v_add_f32_e32 v40, 1.0, v47
	v_rcp_f32_e32 v47, v40
	v_mov_b32_e32 v40, v36
	v_mov_b32_e32 v41, v32
	v_pk_mul_f32 v[40:41], v[40:41], v[54:55] op_sel_hi:[1,0]
	v_mul_f32_e32 v36, v45, v46
	v_mul_f32_e32 v32, 0xbfb8aa3b, v41
	v_exp_f32_e32 v32, v32
	v_mul_f32_e32 v44, v44, v36
	v_mul_f32_e32 v36, v43, v47
	v_mul_f32_e32 v42, v42, v36
	v_add_f32_e32 v32, 1.0, v32
	v_rcp_f32_e32 v43, v32
	v_mov_b32_e32 v32, v37
	v_pk_mul_f32 v[32:33], v[32:33], v[54:55] op_sel_hi:[1,0]
	v_mul_f32_e32 v36, v41, v43
	v_mul_f32_e32 v37, 0xbfb8aa3b, v33
	v_exp_f32_e32 v37, v37
	v_mul_f32_e32 v40, v40, v36
	v_add_f32_e32 v36, 1.0, v37
	v_rcp_f32_e32 v41, v36
	v_mov_b32_e32 v36, v38
	v_mov_b32_e32 v37, v34
	v_pk_mul_f32 v[36:37], v[36:37], v[54:55] op_sel_hi:[1,0]
	v_mul_f32_e32 v33, v33, v41
	v_mul_f32_e32 v34, 0xbfb8aa3b, v37
	v_exp_f32_e32 v38, v34
	v_mov_b32_e32 v34, v39
	v_pk_mul_f32 v[34:35], v[34:35], v[54:55] op_sel_hi:[1,0]
	v_mul_f32_e32 v41, v32, v33
	v_mul_f32_e32 v39, 0xbfb8aa3b, v35
	v_exp_f32_e32 v39, v39
	v_add_f32_e32 v38, 1.0, v38
	v_rcp_f32_e32 v38, v38
	v_add_f32_e32 v39, 1.0, v39
	v_rcp_f32_e32 v39, v39
	v_mul_f32_e32 v32, v37, v38
	v_mul_f32_e32 v36, v36, v32
	v_mul_f32_e32 v32, v35, v39
	v_mul_f32_e32 v35, v34, v32
	v_cvt_pk_bf16_f32 v32, v48, v49
	v_cvt_pk_bf16_f32 v33, v44, v42
	v_cvt_pk_bf16_f32 v34, v40, v41
	v_cvt_pk_bf16_f32 v35, v36, v35
	v_fmamk_f32 v36, v123, 0x3a800000, v154
	v_mul_f32_e32 v37, 0x4b800000, v36
	v_cmp_gt_f32_e32 vcc, s61, v36
	v_mov_b32_e32 v40, v28
	v_mov_b32_e32 v41, v24
	v_cndmask_b32_e32 v36, v36, v37, vcc
	v_rsq_f32_e32 v38, v36
	v_mad_i64_i32 v[36:37], s[26:27], v124, s62, v[112:113]
	v_lshl_add_u64 v[36:37], v[36:37], 0, s[8:9]
	v_mul_f32_e32 v39, 0x45800000, v38
	v_cndmask_b32_e32 v38, v38, v39, vcc
	v_pk_mul_f32 v[40:41], v[40:41], v[38:39] op_sel_hi:[1,0]
	v_lshl_add_u64 v[36:37], v[36:37], 0, s[24:25]
	v_mul_f32_e32 v24, 0xbfb8aa3b, v41
	v_exp_f32_e32 v39, v24
	v_mov_b32_e32 v24, v29
	v_pk_mul_f32 v[24:25], v[24:25], v[38:39] op_sel_hi:[1,0]
	s_nop 0
	v_mul_f32_e32 v28, 0xbfb8aa3b, v25
	v_exp_f32_e32 v42, v28
	v_lshl_add_u64 v[28:29], v[36:37], 0, v[114:115]
	v_add_f32_e32 v36, 1.0, v39
	v_rcp_f32_e32 v36, v36
	global_store_dwordx4 v[28:29], v[32:35], off
	v_mov_b32_e32 v29, v26
	v_add_f32_e32 v37, 1.0, v42
	v_mul_f32_e32 v28, v41, v36
	v_mul_f32_e32 v32, v40, v28
	v_mov_b32_e32 v28, v30
	v_pk_mul_f32 v[28:29], v[28:29], v[38:39] op_sel_hi:[1,0]
	v_rcp_f32_e32 v37, v37
	v_mul_f32_e32 v26, 0xbfb8aa3b, v29
	v_exp_f32_e32 v30, v26
	v_mov_b32_e32 v26, v31
	v_pk_mul_f32 v[26:27], v[26:27], v[38:39] op_sel_hi:[1,0]
	v_mul_f32_e32 v25, v25, v37
	v_mul_f32_e32 v31, 0xbfb8aa3b, v27
	v_exp_f32_e32 v31, v31
	v_mul_f32_e32 v33, v24, v25
	v_add_f32_e32 v24, 1.0, v30
	v_rcp_f32_e32 v30, v24
	v_add_f32_e32 v24, 1.0, v31
	v_rcp_f32_e32 v31, v24
	v_mov_b32_e32 v24, v20
	v_mov_b32_e32 v25, v16
	v_pk_mul_f32 v[24:25], v[24:25], v[38:39] op_sel_hi:[1,0]
	v_mul_f32_e32 v20, v29, v30
	v_mul_f32_e32 v16, 0xbfb8aa3b, v25
	v_exp_f32_e32 v16, v16
	v_mul_f32_e32 v28, v28, v20
	v_mul_f32_e32 v20, v27, v31
	v_mul_f32_e32 v26, v26, v20
	v_add_f32_e32 v16, 1.0, v16
	v_rcp_f32_e32 v27, v16
	v_mov_b32_e32 v16, v21
	v_pk_mul_f32 v[16:17], v[16:17], v[38:39] op_sel_hi:[1,0]
	v_mul_f32_e32 v20, v25, v27
	v_mul_f32_e32 v21, 0xbfb8aa3b, v17
	v_exp_f32_e32 v21, v21
	v_mul_f32_e32 v24, v24, v20
	v_add_f32_e32 v20, 1.0, v21
	v_rcp_f32_e32 v25, v20
	v_mov_b32_e32 v20, v22
	v_mov_b32_e32 v21, v18
	v_pk_mul_f32 v[20:21], v[20:21], v[38:39] op_sel_hi:[1,0]
; __device__ __forceinline__ float siluf_(float x) { return x * sigmoidf_(x); }
; __device__ __forceinline__ float rinv_of(float ssq) { return rsqrtf(ssq * (1.0f / 1024.0f) + EPS); }
; __device__ __forceinline__ u32x4 pack8(const f32x4 a, const f32x4 b) { u32x4 w; w.x = cvt_pk_bf16(a[0], a[1]); w.y = cvt_pk_bf16(a[2], a[3]); w.z = cvt_pk_bf16(b[0], b[1]); w.w = cvt_pk_bf16(b[2], b[3]); return w; }
; template <class Epi>
; __device__ __forceinline__ void gemm_phase(LAS unsigned char* lds, const Gemm g, const StaticOrder& S, const Epi& E) {
;     ...
;         if (!has_next) break;
;     __device__ __forceinline__ void operator()(const AccT& acc, const pg8::Unit& u, int wr, int wc, int fr, int fq) const {
;     ...
;             for (int m = 0; m < 4; ++m) {
;                 const int r = EPI_ROW(u, ai, m); const float ri = rinv_of(ris[ai][m]);
;                 f32x4 o[2];
; #pragma unroll
;                 for (int n = 0; n < 2; ++n) { const f32x4 gt = acc[ai][0][m][n] * ri, up = acc[ai][1][m][n] * ri;
; #pragma unroll
;                     for (int j = 0; j < 4; ++j) o[n][j] = siluf_(gt[j]) * up[j]; }
;                 *(u32x4*)(act + (size_t)r * DFF + u.pn * 128 + wc * 32 + 8 * fq) = pack8(o[0], o[1]); }
	v_mul_f32_e32 v17, v17, v25
	v_mul_f32_e32 v18, 0xbfb8aa3b, v21
	v_exp_f32_e32 v22, v18
	v_mov_b32_e32 v18, v23
	v_pk_mul_f32 v[18:19], v[18:19], v[38:39] op_sel_hi:[1,0]
	v_mul_f32_e32 v25, v16, v17
	v_mul_f32_e32 v23, 0xbfb8aa3b, v19
	v_exp_f32_e32 v23, v23
	v_add_f32_e32 v22, 1.0, v22
	v_rcp_f32_e32 v22, v22
	v_add_f32_e32 v23, 1.0, v23
	v_rcp_f32_e32 v23, v23
	v_mul_f32_e32 v16, v21, v22
	v_mul_f32_e32 v20, v20, v16
	v_mul_f32_e32 v16, v19, v23
	v_mul_f32_e32 v19, v18, v16
	v_cvt_pk_bf16_f32 v16, v32, v33
	v_cvt_pk_bf16_f32 v17, v28, v26
	v_cvt_pk_bf16_f32 v18, v24, v25
	v_cvt_pk_bf16_f32 v19, v20, v19
	v_fmamk_f32 v20, v121, 0x3a800000, v154
	v_mul_f32_e32 v21, 0x4b800000, v20
	v_cmp_gt_f32_e32 vcc, s61, v20
	v_mov_b32_e32 v24, v12
	v_mov_b32_e32 v25, v8
	v_cndmask_b32_e32 v20, v20, v21, vcc
	v_rsq_f32_e32 v22, v20
	v_mad_i64_i32 v[20:21], s[26:27], v122, s62, v[112:113]
	v_lshl_add_u64 v[20:21], v[20:21], 0, s[8:9]
	v_mul_f32_e32 v23, 0x45800000, v22
	v_cndmask_b32_e32 v22, v22, v23, vcc
	v_pk_mul_f32 v[24:25], v[24:25], v[22:23] op_sel_hi:[1,0]
	v_lshl_add_u64 v[20:21], v[20:21], 0, s[24:25]
	v_mul_f32_e32 v8, 0xbfb8aa3b, v25
	v_exp_f32_e32 v23, v8
	v_mov_b32_e32 v8, v13
	s_and_b64 vcc, exec, s[6:7]
	v_pk_mul_f32 v[8:9], v[8:9], v[22:23] op_sel_hi:[1,0]
	s_nop 0
	v_mul_f32_e32 v12, 0xbfb8aa3b, v9
	v_exp_f32_e32 v26, v12
	v_lshl_add_u64 v[12:13], v[20:21], 0, v[114:115]
	v_add_f32_e32 v20, 1.0, v23
	v_rcp_f32_e32 v20, v20
	global_store_dwordx4 v[12:13], v[16:19], off
	v_mov_b32_e32 v13, v10
	v_add_f32_e32 v21, 1.0, v26
	v_mul_f32_e32 v12, v25, v20
	v_mul_f32_e32 v16, v24, v12
	v_mov_b32_e32 v12, v14
	v_pk_mul_f32 v[12:13], v[12:13], v[22:23] op_sel_hi:[1,0]
	v_rcp_f32_e32 v21, v21
	v_mul_f32_e32 v10, 0xbfb8aa3b, v13
	v_exp_f32_e32 v14, v10
	v_mov_b32_e32 v10, v15
	v_pk_mul_f32 v[10:11], v[10:11], v[22:23] op_sel_hi:[1,0]
	v_mul_f32_e32 v9, v9, v21
	v_mul_f32_e32 v15, 0xbfb8aa3b, v11
	v_exp_f32_e32 v15, v15
	v_mul_f32_e32 v17, v8, v9
	v_add_f32_e32 v8, 1.0, v14
	v_rcp_f32_e32 v14, v8
	v_add_f32_e32 v8, 1.0, v15
	v_rcp_f32_e32 v15, v8
	v_mov_b32_e32 v8, v0
	v_mov_b32_e32 v9, v4
	v_pk_mul_f32 v[8:9], v[8:9], v[22:23] op_sel_hi:[1,0]
	v_mul_f32_e32 v4, v13, v14
	v_mul_f32_e32 v0, 0xbfb8aa3b, v9
	v_exp_f32_e32 v0, v0
	v_mul_f32_e32 v12, v12, v4
	v_mov_b32_e32 v4, v1
	v_mul_f32_e32 v11, v11, v15
	v_add_f32_e32 v0, 1.0, v0
	v_rcp_f32_e32 v13, v0
	v_pk_mul_f32 v[0:1], v[4:5], v[22:23] op_sel_hi:[1,0]
	v_mul_f32_e32 v10, v10, v11
	v_mul_f32_e32 v4, 0xbfb8aa3b, v1
	v_exp_f32_e32 v4, v4
	v_mul_f32_e32 v5, v9, v13
	v_mul_f32_e32 v8, v8, v5
	v_mov_b32_e32 v5, v6
	v_add_f32_e32 v4, 1.0, v4
	v_rcp_f32_e32 v9, v4
	v_mov_b32_e32 v4, v2
	v_pk_mul_f32 v[4:5], v[4:5], v[22:23] op_sel_hi:[1,0]
	v_mov_b32_e32 v6, v3
	v_mul_f32_e32 v2, 0xbfb8aa3b, v5
	v_exp_f32_e32 v11, v2
	v_pk_mul_f32 v[2:3], v[6:7], v[22:23] op_sel_hi:[1,0]
	v_mul_f32_e32 v1, v1, v9
	v_mul_f32_e32 v6, 0xbfb8aa3b, v3
	v_exp_f32_e32 v6, v6
	v_add_f32_e32 v7, 1.0, v11
	v_rcp_f32_e32 v7, v7
	v_mul_f32_e32 v9, v0, v1
	v_add_f32_e32 v6, 1.0, v6
	v_rcp_f32_e32 v6, v6
	v_mul_f32_e32 v0, v5, v7
	v_mul_f32_e32 v4, v4, v0
	v_mul_f32_e32 v0, v3, v6
	v_mul_f32_e32 v3, v2, v0
	v_cvt_pk_bf16_f32 v0, v16, v17
	v_cvt_pk_bf16_f32 v1, v12, v10
	v_cvt_pk_bf16_f32 v2, v8, v9
	v_cvt_pk_bf16_f32 v3, v4, v3
	v_mad_i64_i32 v[4:5], s[26:27], v120, s62, v[112:113]
	v_lshl_add_u64 v[4:5], v[4:5], 0, s[8:9]
	v_lshl_add_u64 v[4:5], v[4:5], 0, s[24:25]
	v_lshl_add_u64 v[4:5], v[4:5], 0, v[114:115]
	s_mov_b32 s25, s14
	s_mov_b32 s24, s16
	s_mov_b64 s[26:27], s[22:23]
	global_store_dwordx4 v[4:5], v[0:3], off
	s_cbranch_vccnz .LBB0_1545

; #define PG8_STAGE(bufoff, gbase, voff) do { _Pragma("unroll") for (int _i = 0; _i < 2; ++_i) \
;         __builtin_amdgcn_global_load_lds((const unsigned*)((const char*)(gbase) + (voff)[_i]), (LAS unsigned*)(lds + (bufoff) + ldsw + _i * 8192), 16, 0, 0); } while (0)
; #define PG8_LDA(dst, b, h) do { _Pragma("unroll") for (int m = 0; m < 4; ++m) _Pragma("unroll") for (int k = 0; k < 2; ++k) dst[m][k] = *(const LAS bf16x8*)(lds + PG8_SA(b, h) + aoff + m * 2048 + k * 1024); } while (0)
; #define PG8_LDB(dst, b, h) do { _Pragma("unroll") for (int n = 0; n < 2; ++n) _Pragma("unroll") for (int k = 0; k < 2; ++k) dst[n][k] = *(const LAS bf16x8*)(lds + PG8_SB(b, h) + boff + n * 2048 + k * 1024); } while (0)
; #define PG8_MMA(ai, bj, At, Bt) do { __builtin_amdgcn_s_setprio(1); _Pragma("unroll") for (int m = 0; m < 4; ++m) _Pragma("unroll") for (int n = 0; n < 2; ++n) _Pragma("unroll") for (int k = 0; k < 2; ++k) \
;         acc[ai][bj][m][n] = __builtin_amdgcn_mfma_f32_16x16x32_bf16(Bt[n][k], At[m][k], acc[ai][bj][m][n], 0, 0, 0); __builtin_amdgcn_s_setprio(0); } while (0)
; #define PG8_WAIT_L(n) asm volatile("s_waitcnt lgkmcnt(" #n ")" ::: "memory")
; template <class Epi>
; __device__ __forceinline__ void gemm_phase(LAS unsigned char* lds, const Gemm g, const StaticOrder& S, const Epi& E) {
;     ...
;         for (int t = 0; t < nt; t += 2) {
;             const bool last = (t == nt - 2);
;             const char* a1 = cA + (size_t)(t + 1) * kstep;
;             const char* a2 = last ? nA : cA + (size_t)(t + 2) * kstep; const char* b2 = last ? nB : cB + (size_t)(t + 2) * kstep;
;             const char* a3 = a2 + kstep; const char* b3 = b2 + kstep;
;             PG8_LDB(B0, 0, 0); PG8_SCHED; PG8_LDA(At, 0, 0); PG8_STAGE(PG8_SA(1, 1), a1 + hstepA, voffA);
;             PG8_WAIT_L(8); PG8_BAR; PG8_WAIT_L(0); PG8_MMA(0, 0, At, B0); PG8_BAR; PG8_SCHED;
;             PG8_LDB(B1, 0, 1); PG8_STAGE(PG8_SB(0, 0), b2, voffB);
;             PG8_BAR; PG8_WAIT_L(0); PG8_MMA(0, 1, At, B1); PG8_BAR;
;             PG8_LDA(At, 0, 1); PG8_STAGE(PG8_SA(0, 0), a2, voffA);
;             PG8_BAR; PG8_WAIT_L(0); PG8_MMA(1, 0, At, B0); PG8_BAR; PG8_SCHED;
;     __device__ __forceinline__ void operator()(const AccT& acc, const pg8::Unit& u, int wr, int wc, int fr, int fq) const {
;     ...
;             for (int m = 0; m < 4; ++m) ris[ai][m] = ssq_in[EPI_ROW(u, ai, m)];
.LBB0_1544:
	ds_read_b128 v[144:147], v151
	ds_read_b128 v[156:159], v151 offset:1024
	ds_read_b128 v[160:163], v151 offset:2048
	ds_read_b128 v[164:167], v151 offset:3072
	s_add_i32 s77, s26, 2
	s_add_u32 s27, s8, 0xfffc0080
	s_addc_u32 s28, s9, -1
	s_cmp_eq_u32 s46, s26
	s_cselect_b32 s26, s64, s65
	s_cselect_b32 s29, s15, s28
	s_cselect_b32 s28, s17, s27
	s_cselect_b32 s27, s63, s76
	s_cbranch_scc0 .Lgu2_skip
	s_lshl_b32 s98, s24, 8
	s_lshl_b32 s99, s35, 6
	s_add_i32 s98, s98, s99
	v_add_lshl_u32 v247, v148, s98, 2
	global_load_dword v248, v247, s[20:21]
	global_load_dword v249, v247, s[20:21] offset:64
	global_load_dword v250, v247, s[20:21] offset:128
	global_load_dword v251, v247, s[20:21] offset:192
	global_load_dword v252, v247, s[20:21] offset:512
	global_load_dword v253, v247, s[20:21] offset:576
	global_load_dword v254, v247, s[20:21] offset:640
	global_load_dword v255, v247, s[20:21] offset:704
.Lgu2_skip:
	v_lshl_add_u64 v[200:201], s[8:9], 0, v[136:137]
	s_add_i32 m0, s37, 0xc000
	ds_read_b128 v[168:171], v152
	ds_read_b128 v[172:175], v152 offset:1024
	ds_read_b128 v[176:179], v152 offset:2048
	ds_read_b128 v[180:183], v152 offset:3072
	ds_read_b128 v[184:187], v152 offset:4096
	ds_read_b128 v[188:191], v152 offset:5120
	ds_read_b128 v[192:195], v152 offset:6144
	ds_read_b128 v[196:199], v152 offset:7168
	global_load_lds_dwordx4 v[200:201], off
	v_lshl_add_u64 v[200:201], s[8:9], 0, v[138:139]
	s_add_i32 m0, s37, 0xe000
	s_nop 0
	global_load_lds_dwordx4 v[200:201], off
	s_waitcnt lgkmcnt(8)
	s_barrier
	s_waitcnt lgkmcnt(0)
	s_setprio 1
	s_waitcnt lgkmcnt(0)
	v_mfma_f32_16x16x32_bf16 v[116:119], v[144:147], v[168:171], v[116:119]
	v_mfma_f32_16x16x32_bf16 v[112:115], v[160:163], v[168:171], v[112:115]
	v_mfma_f32_16x16x32_bf16 v[104:107], v[144:147], v[176:179], v[104:107]
	v_mfma_f32_16x16x32_bf16 v[96:99], v[160:163], v[176:179], v[96:99]
	v_mfma_f32_16x16x32_bf16 v[88:91], v[144:147], v[184:187], v[88:91]
	v_mfma_f32_16x16x32_bf16 v[80:83], v[160:163], v[184:187], v[80:83]
	v_mfma_f32_16x16x32_bf16 v[72:75], v[144:147], v[192:195], v[72:75]
	v_mfma_f32_16x16x32_bf16 v[64:67], v[160:163], v[192:195], v[64:67]
	v_mfma_f32_16x16x32_bf16 v[116:119], v[156:159], v[172:175], v[116:119]
	v_mfma_f32_16x16x32_bf16 v[112:115], v[164:167], v[172:175], v[112:115]
	v_mfma_f32_16x16x32_bf16 v[104:107], v[156:159], v[180:183], v[104:107]
	v_mfma_f32_16x16x32_bf16 v[96:99], v[164:167], v[180:183], v[96:99]
	v_mfma_f32_16x16x32_bf16 v[88:91], v[156:159], v[188:191], v[88:91]
	v_mfma_f32_16x16x32_bf16 v[80:83], v[164:167], v[188:191], v[80:83]
	v_mfma_f32_16x16x32_bf16 v[72:75], v[156:159], v[196:199], v[72:75]
	v_mfma_f32_16x16x32_bf16 v[64:67], v[164:167], v[196:199], v[64:67]
	s_setprio 0
	s_barrier
	s_add_i32 s66, s49, s36
	v_lshl_add_u64 v[208:209], s[26:27], 0, v[130:131]
	s_mov_b32 m0, s66
	ds_read_b128 v[200:203], v153
	ds_read_b128 v[204:207], v153 offset:1024
	ds_read_b128 v[212:215], v153 offset:2048
	ds_read_b128 v[216:219], v153 offset:3072
	global_load_lds_dwordx4 v[208:209], off
	v_lshl_add_u64 v[220:221], s[26:27], 0, v[134:135]
	s_add_i32 m0, s66, 0x2000
	s_nop 0
	global_load_lds_dwordx4 v[220:221], off
	s_barrier
	s_waitcnt lgkmcnt(0)
	s_setprio 1
	s_waitcnt lgkmcnt(0)
	v_mfma_f32_16x16x32_bf16 v[124:127], v[200:203], v[168:171], v[124:127]
	v_mfma_f32_16x16x32_bf16 v[120:123], v[212:215], v[168:171], v[120:123]
	v_mfma_f32_16x16x32_bf16 v[108:111], v[200:203], v[176:179], v[108:111]
	v_mfma_f32_16x16x32_bf16 v[100:103], v[212:215], v[176:179], v[100:103]
	v_mfma_f32_16x16x32_bf16 v[92:95], v[200:203], v[184:187], v[92:95]
	v_mfma_f32_16x16x32_bf16 v[84:87], v[212:215], v[184:187], v[84:87]
	v_mfma_f32_16x16x32_bf16 v[76:79], v[200:203], v[192:195], v[76:79]
	v_mfma_f32_16x16x32_bf16 v[68:71], v[212:215], v[192:195], v[68:71]
	v_mfma_f32_16x16x32_bf16 v[124:127], v[204:207], v[172:175], v[124:127]
	v_mfma_f32_16x16x32_bf16 v[120:123], v[216:219], v[172:175], v[120:123]
	v_mfma_f32_16x16x32_bf16 v[108:111], v[204:207], v[180:183], v[108:111]
	v_mfma_f32_16x16x32_bf16 v[100:103], v[216:219], v[180:183], v[100:103]
	v_mfma_f32_16x16x32_bf16 v[92:95], v[204:207], v[188:191], v[92:95]
	v_mfma_f32_16x16x32_bf16 v[84:87], v[216:219], v[188:191], v[84:87]
	v_mfma_f32_16x16x32_bf16 v[76:79], v[204:207], v[196:199], v[76:79]
	v_mfma_f32_16x16x32_bf16 v[68:71], v[216:219], v[196:199], v[68:71]
	s_setprio 0
	s_mov_b32 m0, s37
	v_lshl_add_u64 v[222:223], s[28:29], 0, v[128:129]
	s_barrier
	ds_read_b128 v[168:171], v152 offset:16384
	ds_read_b128 v[172:175], v152 offset:17408
	ds_read_b128 v[176:179], v152 offset:18432
	ds_read_b128 v[180:183], v152 offset:19456
	ds_read_b128 v[184:187], v152 offset:20480
	ds_read_b128 v[188:191], v152 offset:21504
	ds_read_b128 v[192:195], v152 offset:22528
	ds_read_b128 v[196:199], v152 offset:23552
	global_load_lds_dwordx4 v[222:223], off
	v_lshl_add_u64 v[224:225], s[28:29], 0, v[132:133]
	s_mov_b32 m0, s38
	s_nop 0
	global_load_lds_dwordx4 v[224:225], off
	s_barrier
	s_waitcnt lgkmcnt(0)
	s_setprio 1
	s_waitcnt lgkmcnt(0)
	v_mfma_f32_16x16x32_bf16 v[56:59], v[144:147], v[168:171], v[56:59]
	v_mfma_f32_16x16x32_bf16 v[48:51], v[160:163], v[168:171], v[48:51]
	v_mfma_f32_16x16x32_bf16 v[40:43], v[144:147], v[176:179], v[40:43]
	v_mfma_f32_16x16x32_bf16 v[32:35], v[160:163], v[176:179], v[32:35]
	v_mfma_f32_16x16x32_bf16 v[24:27], v[144:147], v[184:187], v[24:27]
	v_mfma_f32_16x16x32_bf16 v[16:19], v[160:163], v[184:187], v[16:19]
	v_mfma_f32_16x16x32_bf16 v[8:11], v[144:147], v[192:195], v[8:11]
	v_mfma_f32_16x16x32_bf16 v[4:7], v[160:163], v[192:195], v[4:7]
	v_mfma_f32_16x16x32_bf16 v[56:59], v[156:159], v[172:175], v[56:59]
	v_mfma_f32_16x16x32_bf16 v[48:51], v[164:167], v[172:175], v[48:51]
	v_mfma_f32_16x16x32_bf16 v[40:43], v[156:159], v[180:183], v[40:43]
	v_mfma_f32_16x16x32_bf16 v[32:35], v[164:167], v[180:183], v[32:35]
	v_mfma_f32_16x16x32_bf16 v[24:27], v[156:159], v[188:191], v[24:27]
	v_mfma_f32_16x16x32_bf16 v[16:19], v[164:167], v[188:191], v[16:19]
	v_mfma_f32_16x16x32_bf16 v[8:11], v[156:159], v[196:199], v[8:11]
	v_mfma_f32_16x16x32_bf16 v[4:7], v[164:167], v[196:199], v[4:7]
	s_setprio 0
	s_barrier
; #define PG8_STAGE(bufoff, gbase, voff) do { _Pragma("unroll") for (int _i = 0; _i < 2; ++_i) \
;         __builtin_amdgcn_global_load_lds((const unsigned*)((const char*)(gbase) + (voff)[_i]), (LAS unsigned*)(lds + (bufoff) + ldsw + _i * 8192), 16, 0, 0); } while (0)
; #define PG8_LDA(dst, b, h) do { _Pragma("unroll") for (int m = 0; m < 4; ++m) _Pragma("unroll") for (int k = 0; k < 2; ++k) dst[m][k] = *(const LAS bf16x8*)(lds + PG8_SA(b, h) + aoff + m * 2048 + k * 1024); } while (0)
; #define PG8_LDB(dst, b, h) do { _Pragma("unroll") for (int n = 0; n < 2; ++n) _Pragma("unroll") for (int k = 0; k < 2; ++k) dst[n][k] = *(const LAS bf16x8*)(lds + PG8_SB(b, h) + boff + n * 2048 + k * 1024); } while (0)
; #define PG8_MMA(ai, bj, At, Bt) do { __builtin_amdgcn_s_setprio(1); _Pragma("unroll") for (int m = 0; m < 4; ++m) _Pragma("unroll") for (int n = 0; n < 2; ++n) _Pragma("unroll") for (int k = 0; k < 2; ++k) \
;         acc[ai][bj][m][n] = __builtin_amdgcn_mfma_f32_16x16x32_bf16(Bt[n][k], At[m][k], acc[ai][bj][m][n], 0, 0, 0); __builtin_amdgcn_s_setprio(0); } while (0)
; #define PG8_WAIT_V(n) asm volatile("s_waitcnt vmcnt(" #n ")" ::: "memory")
; #define PG8_WAIT_L(n) asm volatile("s_waitcnt lgkmcnt(" #n ")" ::: "memory")
; #define PG8_BAR __builtin_amdgcn_s_barrier()
; #define PG8_SCHED __builtin_amdgcn_sched_barrier(0)
; template <class Epi>
; __device__ __forceinline__ void gemm_phase(LAS unsigned char* lds, const Gemm g, const StaticOrder& S, const Epi& E) {
;     ...
;             PG8_STAGE(PG8_SB(0, 1), b2 + hstepB, voffB);
;             PG8_WAIT_V(6); PG8_BAR; PG8_MMA(1, 1, At, B1); PG8_BAR;
;             PG8_LDB(B0, 1, 0); PG8_SCHED; PG8_LDA(At, 1, 0); PG8_STAGE(PG8_SA(0, 1), a2 + hstepA, voffA);
;             PG8_WAIT_L(8); PG8_BAR; PG8_WAIT_L(0); PG8_MMA(0, 0, At, B0); PG8_BAR; PG8_SCHED;
;             PG8_LDB(B1, 1, 1); PG8_STAGE(PG8_SB(1, 0), b3, voffB);
	s_add_u32 s78, s26, 0x40000
	s_addc_u32 s79, s27, 0
	s_add_i32 s66, s60, s36
	v_lshl_add_u64 v[144:145], s[78:79], 0, v[130:131]
	s_mov_b32 m0, s66
	s_nop 0
	global_load_lds_dwordx4 v[144:145], off
	v_lshl_add_u64 v[144:145], s[78:79], 0, v[134:135]
	s_add_i32 m0, s66, 0x2000
	s_nop 0
	global_load_lds_dwordx4 v[144:145], off
	s_waitcnt vmcnt(6)
	s_barrier
	s_setprio 1
	v_mfma_f32_16x16x32_bf16 v[60:63], v[200:203], v[168:171], v[60:63]
	v_mfma_f32_16x16x32_bf16 v[52:55], v[212:215], v[168:171], v[52:55]
	v_mfma_f32_16x16x32_bf16 v[44:47], v[200:203], v[176:179], v[44:47]
	v_mfma_f32_16x16x32_bf16 v[36:39], v[212:215], v[176:179], v[36:39]
	v_mfma_f32_16x16x32_bf16 v[28:31], v[200:203], v[184:187], v[28:31]
	v_mfma_f32_16x16x32_bf16 v[20:23], v[212:215], v[184:187], v[20:23]
	v_mfma_f32_16x16x32_bf16 v[12:15], v[200:203], v[192:195], v[12:15]
	v_mfma_f32_16x16x32_bf16 v[0:3], v[212:215], v[192:195], v[0:3]
	v_mfma_f32_16x16x32_bf16 v[60:63], v[204:207], v[172:175], v[60:63]
	v_mfma_f32_16x16x32_bf16 v[52:55], v[216:219], v[172:175], v[52:55]
	v_mfma_f32_16x16x32_bf16 v[44:47], v[204:207], v[180:183], v[44:47]
	v_mfma_f32_16x16x32_bf16 v[36:39], v[216:219], v[180:183], v[36:39]
	v_mfma_f32_16x16x32_bf16 v[28:31], v[204:207], v[188:191], v[28:31]
	v_mfma_f32_16x16x32_bf16 v[20:23], v[216:219], v[188:191], v[20:23]
	v_mfma_f32_16x16x32_bf16 v[12:15], v[204:207], v[196:199], v[12:15]
	v_mfma_f32_16x16x32_bf16 v[0:3], v[216:219], v[196:199], v[0:3]
	s_setprio 0
	s_add_i32 s66, 0, 0x18000
	v_add_u32_e32 v155, s66, v150
	s_barrier
	ds_read_b128 v[144:147], v155
	ds_read_b128 v[156:159], v155 offset:1024
	ds_read_b128 v[160:163], v155 offset:2048
	ds_read_b128 v[164:167], v155 offset:3072
	s_add_u32 s28, s28, 0x40000
	s_addc_u32 s29, s29, 0
	s_mov_b32 m0, s39
	v_lshl_add_u64 v[200:201], s[28:29], 0, v[128:129]
	ds_read_b128 v[168:171], v152 offset:32768
	ds_read_b128 v[172:175], v152 offset:33792
	ds_read_b128 v[176:179], v152 offset:34816
	ds_read_b128 v[180:183], v152 offset:35840
	ds_read_b128 v[184:187], v152 offset:36864
	ds_read_b128 v[188:191], v152 offset:37888
	ds_read_b128 v[192:195], v152 offset:38912
	ds_read_b128 v[196:199], v152 offset:39936
	global_load_lds_dwordx4 v[200:201], off
	v_lshl_add_u64 v[200:201], s[28:29], 0, v[132:133]
	s_mov_b32 m0, s40
	s_nop 0
	global_load_lds_dwordx4 v[200:201], off
	s_waitcnt lgkmcnt(8)
	s_barrier
	s_waitcnt lgkmcnt(0)
	s_setprio 1
	s_waitcnt lgkmcnt(0)
	v_mfma_f32_16x16x32_bf16 v[116:119], v[144:147], v[168:171], v[116:119]
	v_mfma_f32_16x16x32_bf16 v[112:115], v[160:163], v[168:171], v[112:115]
	v_mfma_f32_16x16x32_bf16 v[104:107], v[144:147], v[176:179], v[104:107]
	v_mfma_f32_16x16x32_bf16 v[96:99], v[160:163], v[176:179], v[96:99]
	v_mfma_f32_16x16x32_bf16 v[88:91], v[144:147], v[184:187], v[88:91]
	v_mfma_f32_16x16x32_bf16 v[80:83], v[160:163], v[184:187], v[80:83]
	v_mfma_f32_16x16x32_bf16 v[72:75], v[144:147], v[192:195], v[72:75]
	v_mfma_f32_16x16x32_bf16 v[64:67], v[160:163], v[192:195], v[64:67]
	v_mfma_f32_16x16x32_bf16 v[116:119], v[156:159], v[172:175], v[116:119]
	v_mfma_f32_16x16x32_bf16 v[112:115], v[164:167], v[172:175], v[112:115]
	v_mfma_f32_16x16x32_bf16 v[104:107], v[156:159], v[180:183], v[104:107]
	v_mfma_f32_16x16x32_bf16 v[96:99], v[164:167], v[180:183], v[96:99]
	v_mfma_f32_16x16x32_bf16 v[88:91], v[156:159], v[188:191], v[88:91]
	v_mfma_f32_16x16x32_bf16 v[80:83], v[164:167], v[188:191], v[80:83]
	v_mfma_f32_16x16x32_bf16 v[72:75], v[156:159], v[196:199], v[72:75]
	v_mfma_f32_16x16x32_bf16 v[64:67], v[164:167], v[196:199], v[64:67]
	s_setprio 0
	s_barrier
	s_add_i32 s28, 0, 0x1c000
	s_add_i32 s29, s66, s36
	v_add_u32_e32 v155, s28, v150
	v_lshl_add_u64 v[208:209], v[208:209], 0, s[10:11]
	s_mov_b32 m0, s29
	ds_read_b128 v[200:203], v155
	ds_read_b128 v[204:207], v155 offset:1024
	ds_read_b128 v[212:215], v155 offset:2048
	ds_read_b128 v[216:219], v155 offset:3072
	global_load_lds_dwordx4 v[208:209], off
	v_lshl_add_u64 v[208:209], v[220:221], 0, s[10:11]
	s_add_i32 m0, s29, 0x2000
	s_nop 0
	global_load_lds_dwordx4 v[208:209], off
	s_barrier
; #define PG8_STAGE(bufoff, gbase, voff) do { _Pragma("unroll") for (int _i = 0; _i < 2; ++_i) \
;         __builtin_amdgcn_global_load_lds((const unsigned*)((const char*)(gbase) + (voff)[_i]), (LAS unsigned*)(lds + (bufoff) + ldsw + _i * 8192), 16, 0, 0); } while (0)
; #define PG8_LDA(dst, b, h) do { _Pragma("unroll") for (int m = 0; m < 4; ++m) _Pragma("unroll") for (int k = 0; k < 2; ++k) dst[m][k] = *(const LAS bf16x8*)(lds + PG8_SA(b, h) + aoff + m * 2048 + k * 1024); } while (0)
; #define PG8_LDB(dst, b, h) do { _Pragma("unroll") for (int n = 0; n < 2; ++n) _Pragma("unroll") for (int k = 0; k < 2; ++k) dst[n][k] = *(const LAS bf16x8*)(lds + PG8_SB(b, h) + boff + n * 2048 + k * 1024); } while (0)
; #define PG8_MMA(ai, bj, At, Bt) do { __builtin_amdgcn_s_setprio(1); _Pragma("unroll") for (int m = 0; m < 4; ++m) _Pragma("unroll") for (int n = 0; n < 2; ++n) _Pragma("unroll") for (int k = 0; k < 2; ++k) \
;         acc[ai][bj][m][n] = __builtin_amdgcn_mfma_f32_16x16x32_bf16(Bt[n][k], At[m][k], acc[ai][bj][m][n], 0, 0, 0); __builtin_amdgcn_s_setprio(0); } while (0)
; #define PG8_WAIT_V(n) asm volatile("s_waitcnt vmcnt(" #n ")" ::: "memory")
; #define PG8_WAIT_L(n) asm volatile("s_waitcnt lgkmcnt(" #n ")" ::: "memory")
; #define PG8_BAR __builtin_amdgcn_s_barrier()
; #define PG8_SCHED __builtin_amdgcn_sched_barrier(0)
; template <class Epi>
; __device__ __forceinline__ void gemm_phase(LAS unsigned char* lds, const Gemm g, const StaticOrder& S, const Epi& E) {
;     ...
;             PG8_LDB(B1, 1, 1); PG8_STAGE(PG8_SB(1, 0), b3, voffB);
;             PG8_BAR; PG8_WAIT_L(0); PG8_MMA(0, 1, At, B1); PG8_BAR;
;             PG8_LDA(At, 1, 1); PG8_STAGE(PG8_SA(1, 0), a3, voffA);
;             PG8_BAR; PG8_WAIT_L(0); PG8_MMA(1, 0, At, B0); PG8_BAR; PG8_SCHED;
;             PG8_STAGE(PG8_SB(1, 1), b3 + hstepB, voffB);
;             PG8_WAIT_V(6); PG8_BAR; PG8_MMA(1, 1, At, B1); PG8_BAR;
	s_waitcnt lgkmcnt(0)
	s_setprio 1
	s_waitcnt lgkmcnt(0)
	v_mfma_f32_16x16x32_bf16 v[124:127], v[200:203], v[168:171], v[124:127]
	v_mfma_f32_16x16x32_bf16 v[120:123], v[212:215], v[168:171], v[120:123]
	v_mfma_f32_16x16x32_bf16 v[108:111], v[200:203], v[176:179], v[108:111]
	v_mfma_f32_16x16x32_bf16 v[100:103], v[212:215], v[176:179], v[100:103]
	v_mfma_f32_16x16x32_bf16 v[92:95], v[200:203], v[184:187], v[92:95]
	v_mfma_f32_16x16x32_bf16 v[84:87], v[212:215], v[184:187], v[84:87]
	v_mfma_f32_16x16x32_bf16 v[76:79], v[200:203], v[192:195], v[76:79]
	v_mfma_f32_16x16x32_bf16 v[68:71], v[212:215], v[192:195], v[68:71]
	v_mfma_f32_16x16x32_bf16 v[124:127], v[204:207], v[172:175], v[124:127]
	v_mfma_f32_16x16x32_bf16 v[120:123], v[216:219], v[172:175], v[120:123]
	v_mfma_f32_16x16x32_bf16 v[108:111], v[204:207], v[180:183], v[108:111]
	v_mfma_f32_16x16x32_bf16 v[100:103], v[216:219], v[180:183], v[100:103]
	v_mfma_f32_16x16x32_bf16 v[92:95], v[204:207], v[188:191], v[92:95]
	v_mfma_f32_16x16x32_bf16 v[84:87], v[216:219], v[188:191], v[84:87]
	v_mfma_f32_16x16x32_bf16 v[76:79], v[204:207], v[196:199], v[76:79]
	v_mfma_f32_16x16x32_bf16 v[68:71], v[216:219], v[196:199], v[68:71]
	s_setprio 0
	s_mov_b32 m0, s44
	v_lshl_add_u64 v[208:209], v[222:223], 0, s[10:11]
	s_barrier
	ds_read_b128 v[168:171], v152 offset:49152
	ds_read_b128 v[172:175], v152 offset:50176
	ds_read_b128 v[176:179], v152 offset:51200
	ds_read_b128 v[180:183], v152 offset:52224
	ds_read_b128 v[184:187], v152 offset:53248
	ds_read_b128 v[188:191], v152 offset:54272
	ds_read_b128 v[192:195], v152 offset:55296
	ds_read_b128 v[196:199], v152 offset:56320
	global_load_lds_dwordx4 v[208:209], off
	v_lshl_add_u64 v[208:209], v[224:225], 0, s[10:11]
	s_mov_b32 m0, s45
	s_nop 0
	global_load_lds_dwordx4 v[208:209], off
	s_barrier
	s_waitcnt lgkmcnt(0)
	s_setprio 1
	s_waitcnt lgkmcnt(0)
	v_mfma_f32_16x16x32_bf16 v[56:59], v[144:147], v[168:171], v[56:59]
	v_mfma_f32_16x16x32_bf16 v[48:51], v[160:163], v[168:171], v[48:51]
	v_mfma_f32_16x16x32_bf16 v[40:43], v[144:147], v[176:179], v[40:43]
	v_mfma_f32_16x16x32_bf16 v[32:35], v[160:163], v[176:179], v[32:35]
	v_mfma_f32_16x16x32_bf16 v[24:27], v[144:147], v[184:187], v[24:27]
	v_mfma_f32_16x16x32_bf16 v[16:19], v[160:163], v[184:187], v[16:19]
	v_mfma_f32_16x16x32_bf16 v[8:11], v[144:147], v[192:195], v[8:11]
	v_mfma_f32_16x16x32_bf16 v[4:7], v[160:163], v[192:195], v[4:7]
	v_mfma_f32_16x16x32_bf16 v[56:59], v[156:159], v[172:175], v[56:59]
	v_mfma_f32_16x16x32_bf16 v[48:51], v[164:167], v[172:175], v[48:51]
	v_mfma_f32_16x16x32_bf16 v[40:43], v[156:159], v[180:183], v[40:43]
	v_mfma_f32_16x16x32_bf16 v[32:35], v[164:167], v[180:183], v[32:35]
	v_mfma_f32_16x16x32_bf16 v[24:27], v[156:159], v[188:191], v[24:27]
	v_mfma_f32_16x16x32_bf16 v[16:19], v[164:167], v[188:191], v[16:19]
	v_mfma_f32_16x16x32_bf16 v[8:11], v[156:159], v[196:199], v[8:11]
	v_mfma_f32_16x16x32_bf16 v[4:7], v[164:167], v[196:199], v[4:7]
	s_setprio 0
	s_barrier
	s_add_u32 s26, s26, 0x40080
	s_addc_u32 s27, s27, 0
	s_add_i32 s28, s28, s36
	v_lshl_add_u64 v[144:145], s[26:27], 0, v[130:131]
	s_mov_b32 m0, s28
	s_nop 0
	global_load_lds_dwordx4 v[144:145], off
	v_lshl_add_u64 v[144:145], s[26:27], 0, v[134:135]
	s_add_i32 m0, s28, 0x2000
	s_nop 0
	global_load_lds_dwordx4 v[144:145], off
	s_waitcnt vmcnt(6)
	s_barrier
	s_setprio 1
	v_mfma_f32_16x16x32_bf16 v[60:63], v[200:203], v[168:171], v[60:63]
	v_mfma_f32_16x16x32_bf16 v[52:55], v[212:215], v[168:171], v[52:55]
	v_mfma_f32_16x16x32_bf16 v[44:47], v[200:203], v[176:179], v[44:47]
	v_mfma_f32_16x16x32_bf16 v[36:39], v[212:215], v[176:179], v[36:39]
	v_mfma_f32_16x16x32_bf16 v[28:31], v[200:203], v[184:187], v[28:31]
	v_mfma_f32_16x16x32_bf16 v[20:23], v[212:215], v[184:187], v[20:23]
	v_mfma_f32_16x16x32_bf16 v[12:15], v[200:203], v[192:195], v[12:15]
	v_mfma_f32_16x16x32_bf16 v[0:3], v[212:215], v[192:195], v[0:3]
	v_mfma_f32_16x16x32_bf16 v[60:63], v[204:207], v[172:175], v[60:63]
	v_mfma_f32_16x16x32_bf16 v[52:55], v[216:219], v[172:175], v[52:55]
	v_mfma_f32_16x16x32_bf16 v[44:47], v[204:207], v[180:183], v[44:47]
	v_mfma_f32_16x16x32_bf16 v[36:39], v[216:219], v[180:183], v[36:39]
	v_mfma_f32_16x16x32_bf16 v[28:31], v[204:207], v[188:191], v[28:31]
	v_mfma_f32_16x16x32_bf16 v[20:23], v[216:219], v[188:191], v[20:23]
	v_mfma_f32_16x16x32_bf16 v[12:15], v[204:207], v[196:199], v[12:15]
	v_mfma_f32_16x16x32_bf16 v[0:3], v[216:219], v[196:199], v[0:3]
	s_setprio 0
	s_add_u32 s8, s8, 0x100
	s_addc_u32 s9, s9, 0
	s_add_u32 s65, s65, 0x100
	s_addc_u32 s76, s76, 0
	s_cmp_ge_i32 s77, s43
	s_mov_b32 s26, s77
	s_barrier
	s_cbranch_scc0 .LBB0_1544
	s_branch .LBB0_1535

; __device__ __forceinline__ float siluf_(float x) { return x * sigmoidf_(x); }
; __device__ __forceinline__ float rinv_of(float ssq) { return rsqrtf(ssq * (1.0f / 1024.0f) + EPS); }
; __device__ __forceinline__ u32x4 pack8(const f32x4 a, const f32x4 b) { u32x4 w; w.x = cvt_pk_bf16(a[0], a[1]); w.y = cvt_pk_bf16(a[2], a[3]); w.z = cvt_pk_bf16(b[0], b[1]); w.w = cvt_pk_bf16(b[2], b[3]); return w; }
;     __device__ __forceinline__ void operator()(const AccT& acc, const pg8::Unit& u, int wr, int wc, int fr, int fq) const {
;         asm volatile("" : "+v"(fr), "+v"(fq), "+s"(wr), "+s"(wc));
;         float ris[2][4];
; #pragma unroll
;         for (int ai = 0; ai < 2; ++ai)
; #pragma unroll
;             for (int m = 0; m < 4; ++m) ris[ai][m] = ssq_in[EPI_ROW(u, ai, m)];
; #pragma unroll
;         for (int ai = 0; ai < 2; ++ai)
; #pragma unroll
;             for (int m = 0; m < 4; ++m) {
;                 const int r = EPI_ROW(u, ai, m); const float ri = rinv_of(ris[ai][m]);
;                 f32x4 o[2];
; #pragma unroll
;                 for (int n = 0; n < 2; ++n) { const f32x4 gt = acc[ai][0][m][n] * ri, up = acc[ai][1][m][n] * ri;
; #pragma unroll
;                     for (int j = 0; j < 4; ++j) o[n][j] = siluf_(gt[j]) * up[j]; }
;                 *(u32x4*)(act + (size_t)r * DFF + u.pn * 128 + wc * 32 + 8 * fq) = pack8(o[0], o[1]); }
.LBB0_2402:
	s_mov_b32 s8, s35
	v_mov_b32_e32 v155, v149
	s_mov_b32 s17, s42
	v_mov_b32_e32 v144, v148
	s_lshl_b32 s9, s24, 8
	s_lshl_b32 s8, s8, 6
	s_add_i32 s8, s8, s9
	v_add_u32_e32 v156, s8, v144
	v_ashrrev_i32_e32 v157, 31, v156
	v_lshl_add_u64 v[144:145], v[156:157], 2, s[10:11]
	v_add_u32_e32 v166, 16, v156
	v_mov_b32_e32 v158, v124
	v_mov_b32_e32 v160, v126
	v_mov_b32_e32 v162, v120
	v_mov_b32_e32 v164, v122
	v_add_u32_e32 v146, 32, v156
	v_add_u32_e32 v144, 48, v156
	v_add_u32_e32 v126, 0x80, v156
	v_add_u32_e32 v124, 0x90, v156
	v_add_u32_e32 v122, 0xa0, v156
	v_add_u32_e32 v120, 0xb0, v156
	v_ashrrev_i32_e32 v167, 31, v166
	v_mov_b32_e32 v159, v116
	v_mov_b32_e32 v116, v125
	v_mov_b32_e32 v161, v118
	v_mov_b32_e32 v118, v127
	v_mov_b32_e32 v163, v112
	v_mov_b32_e32 v112, v121
	v_mov_b32_e32 v165, v114
	v_mov_b32_e32 v114, v123
	v_ashrrev_i32_e32 v147, 31, v146
	v_ashrrev_i32_e32 v145, 31, v144
	v_ashrrev_i32_e32 v127, 31, v126
	v_ashrrev_i32_e32 v125, 31, v124
	v_ashrrev_i32_e32 v123, 31, v122
	v_ashrrev_i32_e32 v121, 31, v120
	v_lshl_add_u64 v[168:169], v[166:167], 2, s[10:11]
	v_lshl_add_u64 v[170:171], v[146:147], 2, s[10:11]
	v_lshl_add_u64 v[172:173], v[144:145], 2, s[10:11]
	v_lshl_add_u64 v[174:175], v[126:127], 2, s[10:11]
	v_lshl_add_u64 v[176:177], v[124:125], 2, s[10:11]
	v_lshl_add_u64 v[178:179], v[122:123], 2, s[10:11]
	v_lshl_add_u64 v[180:181], v[120:121], 2, s[10:11]
	s_lshl_b32 s8, s25, 7
	s_ashr_i32 s9, s8, 31
	s_lshl_b32 s24, s17, 5
	s_ashr_i32 s25, s24, 31
	s_lshl_b64 s[8:9], s[8:9], 1
	s_lshl_b64 s[24:25], s[24:25], 1
	s_mov_b64 s[28:29], s[20:21]
	s_waitcnt vmcnt(16)
	v_mov_b32_e32 v157, v248
	v_mov_b32_e32 v127, v249
	v_mov_b32_e32 v145, v250
	v_mov_b32_e32 v147, v251
	v_mov_b32_e32 v167, v252
	v_mov_b32_e32 v125, v253
	v_mov_b32_e32 v123, v254
	v_mov_b32_e32 v121, v255
	v_fmamk_f32 v157, v157, 0x3a800000, v154
	v_mul_f32_e32 v168, 0x4b800000, v157
	v_cmp_gt_f32_e32 vcc, s61, v157
	v_fmamk_f32 v127, v127, 0x3a800000, v154
	s_nop 0
	v_cndmask_b32_e32 v157, v157, v168, vcc
	v_rsq_f32_e32 v157, v157
	v_lshlrev_b32_e32 v168, 3, v155
	v_ashrrev_i32_e32 v169, 31, v168
	v_mul_f32_e32 v155, 0x45800000, v157
	v_cndmask_b32_e32 v170, v157, v155, vcc
	v_pk_mul_f32 v[158:159], v[158:159], v[170:171] op_sel_hi:[1,0]
	v_pk_mul_f32 v[116:117], v[116:117], v[170:171] op_sel_hi:[1,0]
	v_mul_f32_e32 v155, 0xbfb8aa3b, v159
	v_mul_f32_e32 v157, 0xbfb8aa3b, v117
	v_exp_f32_e32 v155, v155
	v_exp_f32_e32 v157, v157
	v_pk_mul_f32 v[160:161], v[160:161], v[170:171] op_sel_hi:[1,0]
	v_pk_mul_f32 v[118:119], v[118:119], v[170:171] op_sel_hi:[1,0]
	v_pk_mul_f32 v[162:163], v[162:163], v[170:171] op_sel_hi:[1,0]
	v_pk_mul_f32 v[112:113], v[112:113], v[170:171] op_sel_hi:[1,0]
	v_pk_mul_f32 v[164:165], v[164:165], v[170:171] op_sel_hi:[1,0]
	v_pk_mul_f32 v[114:115], v[114:115], v[170:171] op_sel_hi:[1,0]
	v_mul_f32_e32 v170, 0xbfb8aa3b, v161
	v_exp_f32_e32 v170, v170
	v_add_f32_e32 v155, 1.0, v155
	v_add_f32_e32 v157, 1.0, v157
	v_rcp_f32_e32 v155, v155
	v_rcp_f32_e32 v157, v157
	v_mul_f32_e32 v173, 0xbfb8aa3b, v113
	v_mul_f32_e32 v172, 0xbfb8aa3b, v163
	v_mul_f32_e32 v174, 0xbfb8aa3b, v165
	v_exp_f32_e32 v173, v173
	v_add_f32_e32 v170, 1.0, v170
	v_exp_f32_e32 v172, v172
	v_exp_f32_e32 v174, v174
	v_rcp_f32_e32 v170, v170
	v_mul_f32_e32 v155, v159, v155
	v_mul_f32_e32 v117, v117, v157
	v_mul_f32_e32 v155, v158, v155
	v_mul_f32_e32 v116, v116, v117
	v_cvt_pk_bf16_f32 v116, v155, v116
	v_mul_f32_e32 v155, 0x4b800000, v127
	v_cmp_gt_f32_e32 vcc, s61, v127
	v_add_f32_e32 v173, 1.0, v173
	v_mul_f32_e32 v171, 0xbfb8aa3b, v119
	v_cndmask_b32_e32 v127, v127, v155, vcc
	v_add_f32_e32 v172, 1.0, v172
	v_rcp_f32_e32 v173, v173
	v_mul_f32_e32 v157, v161, v170
	v_add_f32_e32 v158, 1.0, v174
	v_rsq_f32_e32 v127, v127
	v_exp_f32_e32 v171, v171
	v_rcp_f32_e32 v172, v172
	v_mul_f32_e32 v117, v160, v157
	v_mul_f32_e32 v157, 0xbfb8aa3b, v115
	v_rcp_f32_e32 v158, v158
	v_exp_f32_e32 v157, v157
	v_mul_f32_e32 v113, v113, v173
	v_mul_f32_e32 v155, 0x45800000, v127
	v_add_f32_e32 v171, 1.0, v171
	v_mul_f32_e32 v159, v163, v172
	v_mul_f32_e32 v112, v112, v113
	v_mul_f32_e32 v113, v165, v158
	v_cndmask_b32_e32 v158, v127, v155, vcc
	v_mov_b32_e32 v160, v108
	v_mov_b32_e32 v161, v104
	v_rcp_f32_e32 v171, v171
	v_add_f32_e32 v157, 1.0, v157
	v_pk_mul_f32 v[160:161], v[160:161], v[158:159] op_sel_hi:[1,0]
	v_rcp_f32_e32 v157, v157
	v_mul_f32_e32 v104, 0xbfb8aa3b, v161
	v_exp_f32_e32 v127, v104
	v_mul_f32_e32 v119, v119, v171
	v_mul_f32_e32 v118, v118, v119
	v_mul_f32_e32 v119, v162, v159
	v_mul_f32_e32 v113, v164, v113
	v_mul_f32_e32 v115, v115, v157
	v_mul_f32_e32 v114, v114, v115
	v_cvt_pk_bf16_f32 v117, v117, v118
	v_cvt_pk_bf16_f32 v118, v119, v112
	v_cvt_pk_bf16_f32 v119, v113, v114
	v_mov_b64_e32 v[112:113], s[74:75]
	v_add_f32_e32 v127, 1.0, v127
	v_mad_i64_i32 v[114:115], s[26:27], v156, s62, v[112:113]
	v_mov_b32_e32 v104, v109
	v_rcp_f32_e32 v127, v127
	v_lshl_add_u64 v[114:115], v[114:115], 0, s[8:9]
	v_pk_mul_f32 v[104:105], v[104:105], v[158:159] op_sel_hi:[1,0]
	v_lshl_add_u64 v[156:157], v[114:115], 0, s[24:25]
	v_lshlrev_b64 v[114:115], 1, v[168:169]
	v_mul_f32_e32 v108, 0xbfb8aa3b, v105
	v_exp_f32_e32 v155, v108
	v_lshl_add_u64 v[108:109], v[156:157], 0, v[114:115]
	global_store_dwordx4 v[108:109], v[116:119], off
	v_mul_f32_e32 v108, v161, v127
	v_mov_b32_e32 v109, v106
	v_mul_f32_e32 v116, v160, v108
	v_mov_b32_e32 v108, v110
	v_pk_mul_f32 v[108:109], v[108:109], v[158:159] op_sel_hi:[1,0]
	v_add_f32_e32 v155, 1.0, v155
	v_mul_f32_e32 v106, 0xbfb8aa3b, v109
	v_exp_f32_e32 v110, v106
	v_mov_b32_e32 v106, v111
	v_rcp_f32_e32 v155, v155
; __device__ __forceinline__ float siluf_(float x) { return x * sigmoidf_(x); }
; __device__ __forceinline__ float rinv_of(float ssq) { return rsqrtf(ssq * (1.0f / 1024.0f) + EPS); }
; __device__ __forceinline__ u32x4 pack8(const f32x4 a, const f32x4 b) { u32x4 w; w.x = cvt_pk_bf16(a[0], a[1]); w.y = cvt_pk_bf16(a[2], a[3]); w.z = cvt_pk_bf16(b[0], b[1]); w.w = cvt_pk_bf16(b[2], b[3]); return w; }
;     __device__ __forceinline__ void operator()(const AccT& acc, const pg8::Unit& u, int wr, int wc, int fr, int fq) const {
;     ...
;             for (int m = 0; m < 4; ++m) {
;                 const int r = EPI_ROW(u, ai, m); const float ri = rinv_of(ris[ai][m]);
;                 f32x4 o[2];
; #pragma unroll
;                 for (int n = 0; n < 2; ++n) { const f32x4 gt = acc[ai][0][m][n] * ri, up = acc[ai][1][m][n] * ri;
; #pragma unroll
;                     for (int j = 0; j < 4; ++j) o[n][j] = siluf_(gt[j]) * up[j]; }
;                 *(u32x4*)(act + (size_t)r * DFF + u.pn * 128 + wc * 32 + 8 * fq) = pack8(o[0], o[1]); }
	v_pk_mul_f32 v[106:107], v[106:107], v[158:159] op_sel_hi:[1,0]
	v_mul_f32_e32 v105, v105, v155
	v_mul_f32_e32 v111, 0xbfb8aa3b, v107
	v_exp_f32_e32 v111, v111
	v_mul_f32_e32 v117, v104, v105
	v_add_f32_e32 v104, 1.0, v110
	v_rcp_f32_e32 v110, v104
	v_add_f32_e32 v104, 1.0, v111
	v_rcp_f32_e32 v111, v104
	v_mov_b32_e32 v104, v100
	v_mov_b32_e32 v105, v96
	v_pk_mul_f32 v[104:105], v[104:105], v[158:159] op_sel_hi:[1,0]
	v_mul_f32_e32 v100, v109, v110
	v_mul_f32_e32 v96, 0xbfb8aa3b, v105
	v_exp_f32_e32 v96, v96
	v_mul_f32_e32 v108, v108, v100
	v_mul_f32_e32 v100, v107, v111
	v_mul_f32_e32 v106, v106, v100
	v_add_f32_e32 v96, 1.0, v96
	v_rcp_f32_e32 v107, v96
	v_mov_b32_e32 v96, v101
	v_pk_mul_f32 v[96:97], v[96:97], v[158:159] op_sel_hi:[1,0]
	v_mul_f32_e32 v100, v105, v107
	v_mul_f32_e32 v101, 0xbfb8aa3b, v97
	v_exp_f32_e32 v101, v101
	v_mul_f32_e32 v104, v104, v100
	v_add_f32_e32 v100, 1.0, v101
	v_rcp_f32_e32 v105, v100
	v_mov_b32_e32 v100, v102
	v_mov_b32_e32 v101, v98
	v_pk_mul_f32 v[100:101], v[100:101], v[158:159] op_sel_hi:[1,0]
	v_mul_f32_e32 v97, v97, v105
	v_mul_f32_e32 v98, 0xbfb8aa3b, v101
	v_exp_f32_e32 v102, v98
	v_mov_b32_e32 v98, v103
	v_pk_mul_f32 v[98:99], v[98:99], v[158:159] op_sel_hi:[1,0]
	v_mul_f32_e32 v105, v96, v97
	v_mul_f32_e32 v103, 0xbfb8aa3b, v99
	v_exp_f32_e32 v103, v103
	v_add_f32_e32 v102, 1.0, v102
	v_rcp_f32_e32 v102, v102
	v_add_f32_e32 v103, 1.0, v103
	v_rcp_f32_e32 v103, v103
	v_mul_f32_e32 v96, v101, v102
	v_mul_f32_e32 v100, v100, v96
	v_mul_f32_e32 v96, v99, v103
	v_mul_f32_e32 v99, v98, v96
	v_cvt_pk_bf16_f32 v96, v116, v117
	v_cvt_pk_bf16_f32 v97, v108, v106
	v_cvt_pk_bf16_f32 v98, v104, v105
	v_cvt_pk_bf16_f32 v99, v100, v99
	v_fmamk_f32 v100, v145, 0x3a800000, v154
	v_mul_f32_e32 v101, 0x4b800000, v100
	v_cmp_gt_f32_e32 vcc, s61, v100
	v_mov_b32_e32 v104, v92
	v_mov_b32_e32 v105, v88
	v_cndmask_b32_e32 v100, v100, v101, vcc
	v_rsq_f32_e32 v102, v100
	v_mad_i64_i32 v[100:101], s[26:27], v166, s62, v[112:113]
	v_lshl_add_u64 v[100:101], v[100:101], 0, s[8:9]
	v_mul_f32_e32 v103, 0x45800000, v102
	v_cndmask_b32_e32 v102, v102, v103, vcc
	v_pk_mul_f32 v[104:105], v[104:105], v[102:103] op_sel_hi:[1,0]
	v_lshl_add_u64 v[100:101], v[100:101], 0, s[24:25]
	v_mul_f32_e32 v88, 0xbfb8aa3b, v105
	v_exp_f32_e32 v103, v88
	v_mov_b32_e32 v88, v93
	v_pk_mul_f32 v[88:89], v[88:89], v[102:103] op_sel_hi:[1,0]
	s_nop 0
	v_mul_f32_e32 v92, 0xbfb8aa3b, v89
	v_exp_f32_e32 v106, v92
	v_lshl_add_u64 v[92:93], v[100:101], 0, v[114:115]
	v_add_f32_e32 v100, 1.0, v103
	v_rcp_f32_e32 v100, v100
	global_store_dwordx4 v[92:93], v[96:99], off
	v_mov_b32_e32 v93, v90
	v_add_f32_e32 v101, 1.0, v106
	v_mul_f32_e32 v92, v105, v100
	v_mul_f32_e32 v96, v104, v92
	v_mov_b32_e32 v92, v94
	v_pk_mul_f32 v[92:93], v[92:93], v[102:103] op_sel_hi:[1,0]
	v_rcp_f32_e32 v101, v101
	v_mul_f32_e32 v90, 0xbfb8aa3b, v93
	v_exp_f32_e32 v94, v90
	v_mov_b32_e32 v90, v95
	v_pk_mul_f32 v[90:91], v[90:91], v[102:103] op_sel_hi:[1,0]
	v_mul_f32_e32 v89, v89, v101
	v_mul_f32_e32 v95, 0xbfb8aa3b, v91
	v_exp_f32_e32 v95, v95
	v_mul_f32_e32 v97, v88, v89
	v_add_f32_e32 v88, 1.0, v94
	v_rcp_f32_e32 v94, v88
	v_add_f32_e32 v88, 1.0, v95
	v_rcp_f32_e32 v95, v88
	v_mov_b32_e32 v88, v84
	v_mov_b32_e32 v89, v80
	v_pk_mul_f32 v[88:89], v[88:89], v[102:103] op_sel_hi:[1,0]
	v_mul_f32_e32 v84, v93, v94
	v_mul_f32_e32 v80, 0xbfb8aa3b, v89
	v_exp_f32_e32 v80, v80
	v_mul_f32_e32 v92, v92, v84
	v_mul_f32_e32 v84, v91, v95
	v_mul_f32_e32 v90, v90, v84
	v_add_f32_e32 v80, 1.0, v80
	v_rcp_f32_e32 v91, v80
	v_mov_b32_e32 v80, v85
	v_pk_mul_f32 v[80:81], v[80:81], v[102:103] op_sel_hi:[1,0]
	v_mul_f32_e32 v84, v89, v91
	v_mul_f32_e32 v85, 0xbfb8aa3b, v81
	v_exp_f32_e32 v85, v85
	v_mul_f32_e32 v88, v88, v84
	v_add_f32_e32 v84, 1.0, v85
	v_rcp_f32_e32 v89, v84
	v_mov_b32_e32 v84, v86
	v_mov_b32_e32 v85, v82
	v_pk_mul_f32 v[84:85], v[84:85], v[102:103] op_sel_hi:[1,0]
	v_mul_f32_e32 v81, v81, v89
	v_mul_f32_e32 v82, 0xbfb8aa3b, v85
	v_exp_f32_e32 v86, v82
	v_mov_b32_e32 v82, v87
	v_pk_mul_f32 v[82:83], v[82:83], v[102:103] op_sel_hi:[1,0]
	v_mul_f32_e32 v89, v80, v81
	v_mul_f32_e32 v87, 0xbfb8aa3b, v83
	v_exp_f32_e32 v87, v87
	v_add_f32_e32 v86, 1.0, v86
	v_rcp_f32_e32 v86, v86
	v_add_f32_e32 v87, 1.0, v87
	v_rcp_f32_e32 v87, v87
	v_mul_f32_e32 v80, v85, v86
	v_mul_f32_e32 v84, v84, v80
	v_mul_f32_e32 v80, v83, v87
	v_mul_f32_e32 v83, v82, v80
	v_cvt_pk_bf16_f32 v80, v96, v97
	v_cvt_pk_bf16_f32 v81, v92, v90
	v_cvt_pk_bf16_f32 v82, v88, v89
	v_cvt_pk_bf16_f32 v83, v84, v83
	v_fmamk_f32 v84, v147, 0x3a800000, v154
	v_mul_f32_e32 v85, 0x4b800000, v84
	v_cmp_gt_f32_e32 vcc, s61, v84
	v_mov_b32_e32 v88, v76
	v_mov_b32_e32 v89, v72
	v_cndmask_b32_e32 v84, v84, v85, vcc
	v_rsq_f32_e32 v86, v84
	v_mad_i64_i32 v[84:85], s[26:27], v146, s62, v[112:113]
	v_lshl_add_u64 v[84:85], v[84:85], 0, s[8:9]
	v_mul_f32_e32 v87, 0x45800000, v86
	v_cndmask_b32_e32 v86, v86, v87, vcc
	v_pk_mul_f32 v[88:89], v[88:89], v[86:87] op_sel_hi:[1,0]
	v_lshl_add_u64 v[84:85], v[84:85], 0, s[24:25]
	v_mul_f32_e32 v72, 0xbfb8aa3b, v89
	v_exp_f32_e32 v87, v72
	v_mov_b32_e32 v72, v77
	v_pk_mul_f32 v[72:73], v[72:73], v[86:87] op_sel_hi:[1,0]
	s_nop 0
	v_mul_f32_e32 v76, 0xbfb8aa3b, v73
	v_exp_f32_e32 v90, v76
	v_lshl_add_u64 v[76:77], v[84:85], 0, v[114:115]
	v_add_f32_e32 v84, 1.0, v87
	v_rcp_f32_e32 v84, v84
	global_store_dwordx4 v[76:77], v[80:83], off
	v_mov_b32_e32 v77, v74
	v_add_f32_e32 v85, 1.0, v90
	v_mul_f32_e32 v76, v89, v84
	v_mul_f32_e32 v80, v88, v76
	v_mov_b32_e32 v76, v78
	v_pk_mul_f32 v[76:77], v[76:77], v[86:87] op_sel_hi:[1,0]
	v_rcp_f32_e32 v85, v85
	v_mul_f32_e32 v74, 0xbfb8aa3b, v77
; __device__ __forceinline__ float siluf_(float x) { return x * sigmoidf_(x); }
; __device__ __forceinline__ float rinv_of(float ssq) { return rsqrtf(ssq * (1.0f / 1024.0f) + EPS); }
; __device__ __forceinline__ u32x4 pack8(const f32x4 a, const f32x4 b) { u32x4 w; w.x = cvt_pk_bf16(a[0], a[1]); w.y = cvt_pk_bf16(a[2], a[3]); w.z = cvt_pk_bf16(b[0], b[1]); w.w = cvt_pk_bf16(b[2], b[3]); return w; }
;     __device__ __forceinline__ void operator()(const AccT& acc, const pg8::Unit& u, int wr, int wc, int fr, int fq) const {
;     ...
;             for (int m = 0; m < 4; ++m) {
;                 const int r = EPI_ROW(u, ai, m); const float ri = rinv_of(ris[ai][m]);
;                 f32x4 o[2];
; #pragma unroll
;                 for (int n = 0; n < 2; ++n) { const f32x4 gt = acc[ai][0][m][n] * ri, up = acc[ai][1][m][n] * ri;
; #pragma unroll
;                     for (int j = 0; j < 4; ++j) o[n][j] = siluf_(gt[j]) * up[j]; }
;                 *(u32x4*)(act + (size_t)r * DFF + u.pn * 128 + wc * 32 + 8 * fq) = pack8(o[0], o[1]); }
	v_exp_f32_e32 v78, v74
	v_mov_b32_e32 v74, v79
	v_pk_mul_f32 v[74:75], v[74:75], v[86:87] op_sel_hi:[1,0]
	v_mul_f32_e32 v73, v73, v85
	v_mul_f32_e32 v79, 0xbfb8aa3b, v75
	v_exp_f32_e32 v79, v79
	v_mul_f32_e32 v81, v72, v73
	v_add_f32_e32 v72, 1.0, v78
	v_rcp_f32_e32 v78, v72
	v_add_f32_e32 v72, 1.0, v79
	v_rcp_f32_e32 v79, v72
	v_mov_b32_e32 v72, v68
	v_mov_b32_e32 v73, v64
	v_pk_mul_f32 v[72:73], v[72:73], v[86:87] op_sel_hi:[1,0]
	v_mul_f32_e32 v68, v77, v78
	v_mul_f32_e32 v64, 0xbfb8aa3b, v73
	v_exp_f32_e32 v64, v64
	v_mul_f32_e32 v76, v76, v68
	v_mul_f32_e32 v68, v75, v79
	v_mul_f32_e32 v74, v74, v68
	v_add_f32_e32 v64, 1.0, v64
	v_rcp_f32_e32 v75, v64
	v_mov_b32_e32 v64, v69
	v_pk_mul_f32 v[64:65], v[64:65], v[86:87] op_sel_hi:[1,0]
	v_mul_f32_e32 v68, v73, v75
	v_mul_f32_e32 v69, 0xbfb8aa3b, v65
	v_exp_f32_e32 v69, v69
	v_mul_f32_e32 v72, v72, v68
	v_add_f32_e32 v68, 1.0, v69
	v_rcp_f32_e32 v73, v68
	v_mov_b32_e32 v68, v70
	v_mov_b32_e32 v69, v66
	v_pk_mul_f32 v[68:69], v[68:69], v[86:87] op_sel_hi:[1,0]
	v_mul_f32_e32 v65, v65, v73
	v_mul_f32_e32 v66, 0xbfb8aa3b, v69
	v_exp_f32_e32 v70, v66
	v_mov_b32_e32 v66, v71
	v_pk_mul_f32 v[66:67], v[66:67], v[86:87] op_sel_hi:[1,0]
	v_mul_f32_e32 v73, v64, v65
	v_mul_f32_e32 v71, 0xbfb8aa3b, v67
	v_exp_f32_e32 v71, v71
	v_add_f32_e32 v70, 1.0, v70
	v_rcp_f32_e32 v70, v70
	v_add_f32_e32 v71, 1.0, v71
	v_rcp_f32_e32 v71, v71
	v_mul_f32_e32 v64, v69, v70
	v_mul_f32_e32 v68, v68, v64
	v_mul_f32_e32 v64, v67, v71
	v_mul_f32_e32 v67, v66, v64
	v_cvt_pk_bf16_f32 v64, v80, v81
	v_cvt_pk_bf16_f32 v65, v76, v74
	v_cvt_pk_bf16_f32 v66, v72, v73
	v_cvt_pk_bf16_f32 v67, v68, v67
	v_fmamk_f32 v68, v167, 0x3a800000, v154
	v_mul_f32_e32 v69, 0x4b800000, v68
	v_cmp_gt_f32_e32 vcc, s61, v68
	v_mov_b32_e32 v72, v60
	v_mov_b32_e32 v73, v56
	v_cndmask_b32_e32 v68, v68, v69, vcc
	v_rsq_f32_e32 v70, v68
	v_mad_i64_i32 v[68:69], s[26:27], v144, s62, v[112:113]
	v_lshl_add_u64 v[68:69], v[68:69], 0, s[8:9]
	v_mul_f32_e32 v71, 0x45800000, v70
	v_cndmask_b32_e32 v70, v70, v71, vcc
	v_pk_mul_f32 v[72:73], v[72:73], v[70:71] op_sel_hi:[1,0]
	v_lshl_add_u64 v[68:69], v[68:69], 0, s[24:25]
	v_mul_f32_e32 v56, 0xbfb8aa3b, v73
	v_exp_f32_e32 v71, v56
	v_mov_b32_e32 v56, v61
	v_pk_mul_f32 v[56:57], v[56:57], v[70:71] op_sel_hi:[1,0]
	s_nop 0
	v_mul_f32_e32 v60, 0xbfb8aa3b, v57
	v_exp_f32_e32 v74, v60
	v_lshl_add_u64 v[60:61], v[68:69], 0, v[114:115]
	v_add_f32_e32 v68, 1.0, v71
	v_rcp_f32_e32 v68, v68
	global_store_dwordx4 v[60:61], v[64:67], off
	v_mov_b32_e32 v61, v58
	v_add_f32_e32 v69, 1.0, v74
	v_mul_f32_e32 v60, v73, v68
	v_mul_f32_e32 v64, v72, v60
	v_mov_b32_e32 v60, v62
	v_pk_mul_f32 v[60:61], v[60:61], v[70:71] op_sel_hi:[1,0]
	v_rcp_f32_e32 v69, v69
	v_mul_f32_e32 v58, 0xbfb8aa3b, v61
	v_exp_f32_e32 v62, v58
	v_mov_b32_e32 v58, v63
	v_pk_mul_f32 v[58:59], v[58:59], v[70:71] op_sel_hi:[1,0]
	v_mul_f32_e32 v57, v57, v69
	v_mul_f32_e32 v63, 0xbfb8aa3b, v59
	v_exp_f32_e32 v63, v63
	v_mul_f32_e32 v65, v56, v57
	v_add_f32_e32 v56, 1.0, v62
	v_rcp_f32_e32 v62, v56
	v_add_f32_e32 v56, 1.0, v63
	v_rcp_f32_e32 v63, v56
	v_mov_b32_e32 v56, v52
	v_mov_b32_e32 v57, v48
	v_pk_mul_f32 v[56:57], v[56:57], v[70:71] op_sel_hi:[1,0]
	v_mul_f32_e32 v52, v61, v62
	v_mul_f32_e32 v48, 0xbfb8aa3b, v57
	v_exp_f32_e32 v48, v48
	v_mul_f32_e32 v60, v60, v52
	v_mul_f32_e32 v52, v59, v63
	v_mul_f32_e32 v58, v58, v52
	v_add_f32_e32 v48, 1.0, v48
	v_rcp_f32_e32 v59, v48
	v_mov_b32_e32 v48, v53
	v_pk_mul_f32 v[48:49], v[48:49], v[70:71] op_sel_hi:[1,0]
	v_mul_f32_e32 v52, v57, v59
	v_mul_f32_e32 v53, 0xbfb8aa3b, v49
	v_exp_f32_e32 v53, v53
	v_mul_f32_e32 v56, v56, v52
	v_add_f32_e32 v52, 1.0, v53
	v_rcp_f32_e32 v57, v52
	v_mov_b32_e32 v52, v54
	v_mov_b32_e32 v53, v50
	v_pk_mul_f32 v[52:53], v[52:53], v[70:71] op_sel_hi:[1,0]
	v_mul_f32_e32 v49, v49, v57
	v_mul_f32_e32 v50, 0xbfb8aa3b, v53
	v_exp_f32_e32 v54, v50
	v_mov_b32_e32 v50, v55
	v_pk_mul_f32 v[50:51], v[50:51], v[70:71] op_sel_hi:[1,0]
	v_mul_f32_e32 v57, v48, v49
	v_mul_f32_e32 v55, 0xbfb8aa3b, v51
	v_exp_f32_e32 v55, v55
	v_add_f32_e32 v54, 1.0, v54
	v_rcp_f32_e32 v54, v54
	v_add_f32_e32 v55, 1.0, v55
	v_rcp_f32_e32 v55, v55
	v_mul_f32_e32 v48, v53, v54
	v_mul_f32_e32 v52, v52, v48
	v_mul_f32_e32 v48, v51, v55
	v_mul_f32_e32 v51, v50, v48
	v_cvt_pk_bf16_f32 v48, v64, v65
	v_cvt_pk_bf16_f32 v49, v60, v58
	v_cvt_pk_bf16_f32 v50, v56, v57
	v_cvt_pk_bf16_f32 v51, v52, v51
	v_fmamk_f32 v52, v125, 0x3a800000, v154
	v_mul_f32_e32 v53, 0x4b800000, v52
	v_cmp_gt_f32_e32 vcc, s61, v52
	v_mov_b32_e32 v56, v44
	v_mov_b32_e32 v57, v40
	v_cndmask_b32_e32 v52, v52, v53, vcc
	v_rsq_f32_e32 v54, v52
	v_mad_i64_i32 v[52:53], s[26:27], v126, s62, v[112:113]
	v_lshl_add_u64 v[52:53], v[52:53], 0, s[8:9]
	v_mul_f32_e32 v55, 0x45800000, v54
	v_cndmask_b32_e32 v54, v54, v55, vcc
	v_pk_mul_f32 v[56:57], v[56:57], v[54:55] op_sel_hi:[1,0]
	v_lshl_add_u64 v[52:53], v[52:53], 0, s[24:25]
	v_mul_f32_e32 v40, 0xbfb8aa3b, v57
	v_exp_f32_e32 v55, v40
	v_mov_b32_e32 v40, v45
	v_pk_mul_f32 v[40:41], v[40:41], v[54:55] op_sel_hi:[1,0]
	s_nop 0
	v_mul_f32_e32 v44, 0xbfb8aa3b, v41
	v_exp_f32_e32 v58, v44
	v_lshl_add_u64 v[44:45], v[52:53], 0, v[114:115]
	v_add_f32_e32 v52, 1.0, v55
	v_rcp_f32_e32 v52, v52
	global_store_dwordx4 v[44:45], v[48:51], off
	v_mov_b32_e32 v45, v42
	v_add_f32_e32 v53, 1.0, v58
	v_mul_f32_e32 v44, v57, v52
	v_mul_f32_e32 v48, v56, v44
	v_mov_b32_e32 v44, v46
	v_pk_mul_f32 v[44:45], v[44:45], v[54:55] op_sel_hi:[1,0]
	v_rcp_f32_e32 v53, v53
	v_mul_f32_e32 v42, 0xbfb8aa3b, v45
	v_exp_f32_e32 v46, v42
	v_mov_b32_e32 v42, v47
	v_pk_mul_f32 v[42:43], v[42:43], v[54:55] op_sel_hi:[1,0]
; __device__ __forceinline__ float siluf_(float x) { return x * sigmoidf_(x); }
; __device__ __forceinline__ float rinv_of(float ssq) { return rsqrtf(ssq * (1.0f / 1024.0f) + EPS); }
; __device__ __forceinline__ u32x4 pack8(const f32x4 a, const f32x4 b) { u32x4 w; w.x = cvt_pk_bf16(a[0], a[1]); w.y = cvt_pk_bf16(a[2], a[3]); w.z = cvt_pk_bf16(b[0], b[1]); w.w = cvt_pk_bf16(b[2], b[3]); return w; }
;     __device__ __forceinline__ void operator()(const AccT& acc, const pg8::Unit& u, int wr, int wc, int fr, int fq) const {
;     ...
;             for (int m = 0; m < 4; ++m) {
;                 const int r = EPI_ROW(u, ai, m); const float ri = rinv_of(ris[ai][m]);
;                 f32x4 o[2];
; #pragma unroll
;                 for (int n = 0; n < 2; ++n) { const f32x4 gt = acc[ai][0][m][n] * ri, up = acc[ai][1][m][n] * ri;
; #pragma unroll
;                     for (int j = 0; j < 4; ++j) o[n][j] = siluf_(gt[j]) * up[j]; }
;                 *(u32x4*)(act + (size_t)r * DFF + u.pn * 128 + wc * 32 + 8 * fq) = pack8(o[0], o[1]); }
	v_mul_f32_e32 v41, v41, v53
	v_mul_f32_e32 v47, 0xbfb8aa3b, v43
	v_exp_f32_e32 v47, v47
	v_mul_f32_e32 v49, v40, v41
	v_add_f32_e32 v40, 1.0, v46
	v_rcp_f32_e32 v46, v40
	v_add_f32_e32 v40, 1.0, v47
	v_rcp_f32_e32 v47, v40
	v_mov_b32_e32 v40, v36
	v_mov_b32_e32 v41, v32
	v_pk_mul_f32 v[40:41], v[40:41], v[54:55] op_sel_hi:[1,0]
	v_mul_f32_e32 v36, v45, v46
	v_mul_f32_e32 v32, 0xbfb8aa3b, v41
	v_exp_f32_e32 v32, v32
	v_mul_f32_e32 v44, v44, v36
	v_mul_f32_e32 v36, v43, v47
	v_mul_f32_e32 v42, v42, v36
	v_add_f32_e32 v32, 1.0, v32
	v_rcp_f32_e32 v43, v32
	v_mov_b32_e32 v32, v37
	v_pk_mul_f32 v[32:33], v[32:33], v[54:55] op_sel_hi:[1,0]
	v_mul_f32_e32 v36, v41, v43
	v_mul_f32_e32 v37, 0xbfb8aa3b, v33
	v_exp_f32_e32 v37, v37
	v_mul_f32_e32 v40, v40, v36
	v_add_f32_e32 v36, 1.0, v37
	v_rcp_f32_e32 v41, v36
	v_mov_b32_e32 v36, v38
	v_mov_b32_e32 v37, v34
	v_pk_mul_f32 v[36:37], v[36:37], v[54:55] op_sel_hi:[1,0]
	v_mul_f32_e32 v33, v33, v41
	v_mul_f32_e32 v34, 0xbfb8aa3b, v37
	v_exp_f32_e32 v38, v34
	v_mov_b32_e32 v34, v39
	v_pk_mul_f32 v[34:35], v[34:35], v[54:55] op_sel_hi:[1,0]
	v_mul_f32_e32 v41, v32, v33
	v_mul_f32_e32 v39, 0xbfb8aa3b, v35
	v_exp_f32_e32 v39, v39
	v_add_f32_e32 v38, 1.0, v38
	v_rcp_f32_e32 v38, v38
	v_add_f32_e32 v39, 1.0, v39
	v_rcp_f32_e32 v39, v39
	v_mul_f32_e32 v32, v37, v38
	v_mul_f32_e32 v36, v36, v32
	v_mul_f32_e32 v32, v35, v39
	v_mul_f32_e32 v35, v34, v32
	v_cvt_pk_bf16_f32 v32, v48, v49
	v_cvt_pk_bf16_f32 v33, v44, v42
	v_cvt_pk_bf16_f32 v34, v40, v41
	v_cvt_pk_bf16_f32 v35, v36, v35
	v_fmamk_f32 v36, v123, 0x3a800000, v154
	v_mul_f32_e32 v37, 0x4b800000, v36
	v_cmp_gt_f32_e32 vcc, s61, v36
	v_mov_b32_e32 v40, v28
	v_mov_b32_e32 v41, v24
	v_cndmask_b32_e32 v36, v36, v37, vcc
	v_rsq_f32_e32 v38, v36
	v_mad_i64_i32 v[36:37], s[26:27], v124, s62, v[112:113]
	v_lshl_add_u64 v[36:37], v[36:37], 0, s[8:9]
	v_mul_f32_e32 v39, 0x45800000, v38
	v_cndmask_b32_e32 v38, v38, v39, vcc
	v_pk_mul_f32 v[40:41], v[40:41], v[38:39] op_sel_hi:[1,0]
	v_lshl_add_u64 v[36:37], v[36:37], 0, s[24:25]
	v_mul_f32_e32 v24, 0xbfb8aa3b, v41
	v_exp_f32_e32 v39, v24
	v_mov_b32_e32 v24, v29
	v_pk_mul_f32 v[24:25], v[24:25], v[38:39] op_sel_hi:[1,0]
	s_nop 0
	v_mul_f32_e32 v28, 0xbfb8aa3b, v25
	v_exp_f32_e32 v42, v28
	v_lshl_add_u64 v[28:29], v[36:37], 0, v[114:115]
	v_add_f32_e32 v36, 1.0, v39
	v_rcp_f32_e32 v36, v36
	global_store_dwordx4 v[28:29], v[32:35], off
	v_mov_b32_e32 v29, v26
	v_add_f32_e32 v37, 1.0, v42
	v_mul_f32_e32 v28, v41, v36
	v_mul_f32_e32 v32, v40, v28
	v_mov_b32_e32 v28, v30
	v_pk_mul_f32 v[28:29], v[28:29], v[38:39] op_sel_hi:[1,0]
	v_rcp_f32_e32 v37, v37
	v_mul_f32_e32 v26, 0xbfb8aa3b, v29
	v_exp_f32_e32 v30, v26
	v_mov_b32_e32 v26, v31
	v_pk_mul_f32 v[26:27], v[26:27], v[38:39] op_sel_hi:[1,0]
	v_mul_f32_e32 v25, v25, v37
	v_mul_f32_e32 v31, 0xbfb8aa3b, v27
	v_exp_f32_e32 v31, v31
	v_mul_f32_e32 v33, v24, v25
	v_add_f32_e32 v24, 1.0, v30
	v_rcp_f32_e32 v30, v24
	v_add_f32_e32 v24, 1.0, v31
	v_rcp_f32_e32 v31, v24
	v_mov_b32_e32 v24, v20
	v_mov_b32_e32 v25, v16
	v_pk_mul_f32 v[24:25], v[24:25], v[38:39] op_sel_hi:[1,0]
	v_mul_f32_e32 v20, v29, v30
	v_mul_f32_e32 v16, 0xbfb8aa3b, v25
	v_exp_f32_e32 v16, v16
	v_mul_f32_e32 v28, v28, v20
	v_mul_f32_e32 v20, v27, v31
	v_mul_f32_e32 v26, v26, v20
	v_add_f32_e32 v16, 1.0, v16
	v_rcp_f32_e32 v27, v16
	v_mov_b32_e32 v16, v21
	v_pk_mul_f32 v[16:17], v[16:17], v[38:39] op_sel_hi:[1,0]
	v_mul_f32_e32 v20, v25, v27
	v_mul_f32_e32 v21, 0xbfb8aa3b, v17
	v_exp_f32_e32 v21, v21
	v_mul_f32_e32 v24, v24, v20
	v_add_f32_e32 v20, 1.0, v21
	v_rcp_f32_e32 v25, v20
	v_mov_b32_e32 v20, v22
	v_mov_b32_e32 v21, v18
	v_pk_mul_f32 v[20:21], v[20:21], v[38:39] op_sel_hi:[1,0]
; __device__ __forceinline__ float siluf_(float x) { return x * sigmoidf_(x); }
; __device__ __forceinline__ float rinv_of(float ssq) { return rsqrtf(ssq * (1.0f / 1024.0f) + EPS); }
; __device__ __forceinline__ u32x4 pack8(const f32x4 a, const f32x4 b) { u32x4 w; w.x = cvt_pk_bf16(a[0], a[1]); w.y = cvt_pk_bf16(a[2], a[3]); w.z = cvt_pk_bf16(b[0], b[1]); w.w = cvt_pk_bf16(b[2], b[3]); return w; }
; template <class Epi>
; __device__ __forceinline__ void gemm_phase(LAS unsigned char* lds, const Gemm g, const StaticOrder& S, const Epi& E) {
;     ...
;         if (!has_next) break;
;     __device__ __forceinline__ void operator()(const AccT& acc, const pg8::Unit& u, int wr, int wc, int fr, int fq) const {
;     ...
;             for (int m = 0; m < 4; ++m) {
;                 const int r = EPI_ROW(u, ai, m); const float ri = rinv_of(ris[ai][m]);
;                 f32x4 o[2];
; #pragma unroll
;                 for (int n = 0; n < 2; ++n) { const f32x4 gt = acc[ai][0][m][n] * ri, up = acc[ai][1][m][n] * ri;
; #pragma unroll
;                     for (int j = 0; j < 4; ++j) o[n][j] = siluf_(gt[j]) * up[j]; }
;                 *(u32x4*)(act + (size_t)r * DFF + u.pn * 128 + wc * 32 + 8 * fq) = pack8(o[0], o[1]); }
	v_mul_f32_e32 v17, v17, v25
	v_mul_f32_e32 v18, 0xbfb8aa3b, v21
	v_exp_f32_e32 v22, v18
	v_mov_b32_e32 v18, v23
	v_pk_mul_f32 v[18:19], v[18:19], v[38:39] op_sel_hi:[1,0]
	v_mul_f32_e32 v25, v16, v17
	v_mul_f32_e32 v23, 0xbfb8aa3b, v19
	v_exp_f32_e32 v23, v23
	v_add_f32_e32 v22, 1.0, v22
	v_rcp_f32_e32 v22, v22
	v_add_f32_e32 v23, 1.0, v23
	v_rcp_f32_e32 v23, v23
	v_mul_f32_e32 v16, v21, v22
	v_mul_f32_e32 v20, v20, v16
	v_mul_f32_e32 v16, v19, v23
	v_mul_f32_e32 v19, v18, v16
	v_cvt_pk_bf16_f32 v16, v32, v33
	v_cvt_pk_bf16_f32 v17, v28, v26
	v_cvt_pk_bf16_f32 v18, v24, v25
	v_cvt_pk_bf16_f32 v19, v20, v19
	v_fmamk_f32 v20, v121, 0x3a800000, v154
	v_mul_f32_e32 v21, 0x4b800000, v20
	v_cmp_gt_f32_e32 vcc, s61, v20
	v_mov_b32_e32 v24, v12
	v_mov_b32_e32 v25, v8
	v_cndmask_b32_e32 v20, v20, v21, vcc
	v_rsq_f32_e32 v22, v20
	v_mad_i64_i32 v[20:21], s[26:27], v122, s62, v[112:113]
	v_lshl_add_u64 v[20:21], v[20:21], 0, s[8:9]
	v_mul_f32_e32 v23, 0x45800000, v22
	v_cndmask_b32_e32 v22, v22, v23, vcc
	v_pk_mul_f32 v[24:25], v[24:25], v[22:23] op_sel_hi:[1,0]
	v_lshl_add_u64 v[20:21], v[20:21], 0, s[24:25]
	v_mul_f32_e32 v8, 0xbfb8aa3b, v25
	v_exp_f32_e32 v23, v8
	v_mov_b32_e32 v8, v13
	s_and_b64 vcc, exec, s[6:7]
	v_pk_mul_f32 v[8:9], v[8:9], v[22:23] op_sel_hi:[1,0]
	s_nop 0
	v_mul_f32_e32 v12, 0xbfb8aa3b, v9
	v_exp_f32_e32 v26, v12
	v_lshl_add_u64 v[12:13], v[20:21], 0, v[114:115]
	v_add_f32_e32 v20, 1.0, v23
	v_rcp_f32_e32 v20, v20
	global_store_dwordx4 v[12:13], v[16:19], off
	v_mov_b32_e32 v13, v10
	v_add_f32_e32 v21, 1.0, v26
	v_mul_f32_e32 v12, v25, v20
	v_mul_f32_e32 v16, v24, v12
	v_mov_b32_e32 v12, v14
	v_pk_mul_f32 v[12:13], v[12:13], v[22:23] op_sel_hi:[1,0]
	v_rcp_f32_e32 v21, v21
	v_mul_f32_e32 v10, 0xbfb8aa3b, v13
	v_exp_f32_e32 v14, v10
	v_mov_b32_e32 v10, v15
	v_pk_mul_f32 v[10:11], v[10:11], v[22:23] op_sel_hi:[1,0]
	v_mul_f32_e32 v9, v9, v21
	v_mul_f32_e32 v15, 0xbfb8aa3b, v11
	v_exp_f32_e32 v15, v15
	v_mul_f32_e32 v17, v8, v9
	v_add_f32_e32 v8, 1.0, v14
	v_rcp_f32_e32 v14, v8
	v_add_f32_e32 v8, 1.0, v15
	v_rcp_f32_e32 v15, v8
	v_mov_b32_e32 v8, v0
	v_mov_b32_e32 v9, v4
	v_pk_mul_f32 v[8:9], v[8:9], v[22:23] op_sel_hi:[1,0]
	v_mul_f32_e32 v4, v13, v14
	v_mul_f32_e32 v0, 0xbfb8aa3b, v9
	v_exp_f32_e32 v0, v0
	v_mul_f32_e32 v12, v12, v4
	v_mov_b32_e32 v4, v1
	v_mul_f32_e32 v11, v11, v15
	v_add_f32_e32 v0, 1.0, v0
	v_rcp_f32_e32 v13, v0
	v_pk_mul_f32 v[0:1], v[4:5], v[22:23] op_sel_hi:[1,0]
	v_mul_f32_e32 v10, v10, v11
	v_mul_f32_e32 v4, 0xbfb8aa3b, v1
	v_exp_f32_e32 v4, v4
	v_mul_f32_e32 v5, v9, v13
	v_mul_f32_e32 v8, v8, v5
	v_mov_b32_e32 v5, v6
	v_add_f32_e32 v4, 1.0, v4
	v_rcp_f32_e32 v9, v4
	v_mov_b32_e32 v4, v2
	v_pk_mul_f32 v[4:5], v[4:5], v[22:23] op_sel_hi:[1,0]
	v_mov_b32_e32 v6, v3
	v_mul_f32_e32 v2, 0xbfb8aa3b, v5
	v_exp_f32_e32 v11, v2
	v_pk_mul_f32 v[2:3], v[6:7], v[22:23] op_sel_hi:[1,0]
	v_mul_f32_e32 v1, v1, v9
	v_mul_f32_e32 v6, 0xbfb8aa3b, v3
	v_exp_f32_e32 v6, v6
	v_add_f32_e32 v7, 1.0, v11
	v_rcp_f32_e32 v7, v7
	v_mul_f32_e32 v9, v0, v1
	v_add_f32_e32 v6, 1.0, v6
	v_rcp_f32_e32 v6, v6
	v_mul_f32_e32 v0, v5, v7
	v_mul_f32_e32 v4, v4, v0
	v_mul_f32_e32 v0, v3, v6
	v_mul_f32_e32 v3, v2, v0
	v_cvt_pk_bf16_f32 v0, v16, v17
	v_cvt_pk_bf16_f32 v1, v12, v10
	v_cvt_pk_bf16_f32 v2, v8, v9
	v_cvt_pk_bf16_f32 v3, v4, v3
	v_mad_i64_i32 v[4:5], s[26:27], v120, s62, v[112:113]
	v_lshl_add_u64 v[4:5], v[4:5], 0, s[8:9]
	v_lshl_add_u64 v[4:5], v[4:5], 0, s[24:25]
	v_lshl_add_u64 v[4:5], v[4:5], 0, v[114:115]
	s_mov_b32 s25, s16
	s_mov_b32 s24, s18
	s_mov_b64 s[26:27], s[22:23]
	global_store_dwordx4 v[4:5], v[0:3], off
	s_cbranch_vccnz .LBB0_2412

; #define PG8_STAGE(bufoff, gbase, voff) do { _Pragma("unroll") for (int _i = 0; _i < 2; ++_i) \
;         __builtin_amdgcn_global_load_lds((const unsigned*)((const char*)(gbase) + (voff)[_i]), (LAS unsigned*)(lds + (bufoff) + ldsw + _i * 8192), 16, 0, 0); } while (0)
; #define PG8_LDA(dst, b, h) do { _Pragma("unroll") for (int m = 0; m < 4; ++m) _Pragma("unroll") for (int k = 0; k < 2; ++k) dst[m][k] = *(const LAS bf16x8*)(lds + PG8_SA(b, h) + aoff + m * 2048 + k * 1024); } while (0)
; #define PG8_LDB(dst, b, h) do { _Pragma("unroll") for (int n = 0; n < 2; ++n) _Pragma("unroll") for (int k = 0; k < 2; ++k) dst[n][k] = *(const LAS bf16x8*)(lds + PG8_SB(b, h) + boff + n * 2048 + k * 1024); } while (0)
; #define PG8_MMA(ai, bj, At, Bt) do { __builtin_amdgcn_s_setprio(1); _Pragma("unroll") for (int m = 0; m < 4; ++m) _Pragma("unroll") for (int n = 0; n < 2; ++n) _Pragma("unroll") for (int k = 0; k < 2; ++k) \
;         acc[ai][bj][m][n] = __builtin_amdgcn_mfma_f32_16x16x32_bf16(Bt[n][k], At[m][k], acc[ai][bj][m][n], 0, 0, 0); __builtin_amdgcn_s_setprio(0); } while (0)
; #define PG8_WAIT_L(n) asm volatile("s_waitcnt lgkmcnt(" #n ")" ::: "memory")
; template <class Epi>
; __device__ __forceinline__ void gemm_phase(LAS unsigned char* lds, const Gemm g, const StaticOrder& S, const Epi& E) {
;     ...
;         for (int t = 0; t < nt; t += 2) {
;             const bool last = (t == nt - 2);
;             const char* a1 = cA + (size_t)(t + 1) * kstep;
;             const char* a2 = last ? nA : cA + (size_t)(t + 2) * kstep; const char* b2 = last ? nB : cB + (size_t)(t + 2) * kstep;
;             const char* a3 = a2 + kstep; const char* b3 = b2 + kstep;
;             PG8_LDB(B0, 0, 0); PG8_SCHED; PG8_LDA(At, 0, 0); PG8_STAGE(PG8_SA(1, 1), a1 + hstepA, voffA);
;             PG8_WAIT_L(8); PG8_BAR; PG8_WAIT_L(0); PG8_MMA(0, 0, At, B0); PG8_BAR; PG8_SCHED;
;             PG8_LDB(B1, 0, 1); PG8_STAGE(PG8_SB(0, 0), b2, voffB);
;             PG8_BAR; PG8_WAIT_L(0); PG8_MMA(0, 1, At, B1); PG8_BAR;
;             PG8_LDA(At, 0, 1); PG8_STAGE(PG8_SA(0, 0), a2, voffA);
;             PG8_BAR; PG8_WAIT_L(0); PG8_MMA(1, 0, At, B0); PG8_BAR; PG8_SCHED;
;     __device__ __forceinline__ void operator()(const AccT& acc, const pg8::Unit& u, int wr, int wc, int fr, int fq) const {
;     ...
;             for (int m = 0; m < 4; ++m) ris[ai][m] = ssq_in[EPI_ROW(u, ai, m)];
.LBB0_2411:
	ds_read_b128 v[144:147], v151
	ds_read_b128 v[156:159], v151 offset:1024
	ds_read_b128 v[160:163], v151 offset:2048
	ds_read_b128 v[164:167], v151 offset:3072
	s_add_i32 s77, s26, 2
	s_add_u32 s27, s8, 0xfffc0080
	s_addc_u32 s28, s9, -1
	s_cmp_eq_u32 s46, s26
	s_cselect_b32 s26, s64, s65
	s_cselect_b32 s29, s17, s28
	s_cselect_b32 s28, s19, s27
	s_cselect_b32 s27, s63, s76
	s_cbranch_scc0 .Lgu10_skip
	s_lshl_b32 s98, s24, 8
	s_lshl_b32 s99, s35, 6
	s_add_i32 s98, s98, s99
	v_add_lshl_u32 v247, v148, s98, 2
	global_load_dword v248, v247, s[10:11]
	global_load_dword v249, v247, s[10:11] offset:64
	global_load_dword v250, v247, s[10:11] offset:128
	global_load_dword v251, v247, s[10:11] offset:192
	global_load_dword v252, v247, s[10:11] offset:512
	global_load_dword v253, v247, s[10:11] offset:576
	global_load_dword v254, v247, s[10:11] offset:640
	global_load_dword v255, v247, s[10:11] offset:704
.Lgu10_skip:
	v_lshl_add_u64 v[200:201], s[8:9], 0, v[136:137]
	s_add_i32 m0, s37, 0xc000
	ds_read_b128 v[168:171], v152
	ds_read_b128 v[172:175], v152 offset:1024
	ds_read_b128 v[176:179], v152 offset:2048
	ds_read_b128 v[180:183], v152 offset:3072
	ds_read_b128 v[184:187], v152 offset:4096
	ds_read_b128 v[188:191], v152 offset:5120
	ds_read_b128 v[192:195], v152 offset:6144
	ds_read_b128 v[196:199], v152 offset:7168
	global_load_lds_dwordx4 v[200:201], off
	v_lshl_add_u64 v[200:201], s[8:9], 0, v[138:139]
	s_add_i32 m0, s37, 0xe000
	s_nop 0
	global_load_lds_dwordx4 v[200:201], off
	s_waitcnt lgkmcnt(8)
	s_barrier
	s_waitcnt lgkmcnt(0)
	s_setprio 1
	s_waitcnt lgkmcnt(0)
	v_mfma_f32_16x16x32_bf16 v[116:119], v[144:147], v[168:171], v[116:119]
	v_mfma_f32_16x16x32_bf16 v[112:115], v[160:163], v[168:171], v[112:115]
	v_mfma_f32_16x16x32_bf16 v[104:107], v[144:147], v[176:179], v[104:107]
	v_mfma_f32_16x16x32_bf16 v[96:99], v[160:163], v[176:179], v[96:99]
	v_mfma_f32_16x16x32_bf16 v[88:91], v[144:147], v[184:187], v[88:91]
	v_mfma_f32_16x16x32_bf16 v[80:83], v[160:163], v[184:187], v[80:83]
	v_mfma_f32_16x16x32_bf16 v[72:75], v[144:147], v[192:195], v[72:75]
	v_mfma_f32_16x16x32_bf16 v[64:67], v[160:163], v[192:195], v[64:67]
	v_mfma_f32_16x16x32_bf16 v[116:119], v[156:159], v[172:175], v[116:119]
	v_mfma_f32_16x16x32_bf16 v[112:115], v[164:167], v[172:175], v[112:115]
	v_mfma_f32_16x16x32_bf16 v[104:107], v[156:159], v[180:183], v[104:107]
	v_mfma_f32_16x16x32_bf16 v[96:99], v[164:167], v[180:183], v[96:99]
	v_mfma_f32_16x16x32_bf16 v[88:91], v[156:159], v[188:191], v[88:91]
	v_mfma_f32_16x16x32_bf16 v[80:83], v[164:167], v[188:191], v[80:83]
	v_mfma_f32_16x16x32_bf16 v[72:75], v[156:159], v[196:199], v[72:75]
	v_mfma_f32_16x16x32_bf16 v[64:67], v[164:167], v[196:199], v[64:67]
	s_setprio 0
	s_barrier
	s_add_i32 s66, s49, s36
	v_lshl_add_u64 v[208:209], s[26:27], 0, v[130:131]
	s_mov_b32 m0, s66
	ds_read_b128 v[200:203], v153
	ds_read_b128 v[204:207], v153 offset:1024
	ds_read_b128 v[212:215], v153 offset:2048
	ds_read_b128 v[216:219], v153 offset:3072
	global_load_lds_dwordx4 v[208:209], off
	v_lshl_add_u64 v[220:221], s[26:27], 0, v[134:135]
	s_add_i32 m0, s66, 0x2000
	s_nop 0
	global_load_lds_dwordx4 v[220:221], off
	s_barrier
	s_waitcnt lgkmcnt(0)
	s_setprio 1
	s_waitcnt lgkmcnt(0)
	v_mfma_f32_16x16x32_bf16 v[124:127], v[200:203], v[168:171], v[124:127]
	v_mfma_f32_16x16x32_bf16 v[120:123], v[212:215], v[168:171], v[120:123]
	v_mfma_f32_16x16x32_bf16 v[108:111], v[200:203], v[176:179], v[108:111]
	v_mfma_f32_16x16x32_bf16 v[100:103], v[212:215], v[176:179], v[100:103]
	v_mfma_f32_16x16x32_bf16 v[92:95], v[200:203], v[184:187], v[92:95]
	v_mfma_f32_16x16x32_bf16 v[84:87], v[212:215], v[184:187], v[84:87]
	v_mfma_f32_16x16x32_bf16 v[76:79], v[200:203], v[192:195], v[76:79]
	v_mfma_f32_16x16x32_bf16 v[68:71], v[212:215], v[192:195], v[68:71]
	v_mfma_f32_16x16x32_bf16 v[124:127], v[204:207], v[172:175], v[124:127]
	v_mfma_f32_16x16x32_bf16 v[120:123], v[216:219], v[172:175], v[120:123]
	v_mfma_f32_16x16x32_bf16 v[108:111], v[204:207], v[180:183], v[108:111]
	v_mfma_f32_16x16x32_bf16 v[100:103], v[216:219], v[180:183], v[100:103]
	v_mfma_f32_16x16x32_bf16 v[92:95], v[204:207], v[188:191], v[92:95]
	v_mfma_f32_16x16x32_bf16 v[84:87], v[216:219], v[188:191], v[84:87]
	v_mfma_f32_16x16x32_bf16 v[76:79], v[204:207], v[196:199], v[76:79]
	v_mfma_f32_16x16x32_bf16 v[68:71], v[216:219], v[196:199], v[68:71]
	s_setprio 0
	s_mov_b32 m0, s37
	v_lshl_add_u64 v[222:223], s[28:29], 0, v[128:129]
	s_barrier
	ds_read_b128 v[168:171], v152 offset:16384
	ds_read_b128 v[172:175], v152 offset:17408
	ds_read_b128 v[176:179], v152 offset:18432
	ds_read_b128 v[180:183], v152 offset:19456
	ds_read_b128 v[184:187], v152 offset:20480
	ds_read_b128 v[188:191], v152 offset:21504
	ds_read_b128 v[192:195], v152 offset:22528
	ds_read_b128 v[196:199], v152 offset:23552
	global_load_lds_dwordx4 v[222:223], off
	v_lshl_add_u64 v[224:225], s[28:29], 0, v[132:133]
	s_mov_b32 m0, s38
	s_nop 0
	global_load_lds_dwordx4 v[224:225], off
	s_barrier
	s_waitcnt lgkmcnt(0)
	s_setprio 1
	s_waitcnt lgkmcnt(0)
	v_mfma_f32_16x16x32_bf16 v[56:59], v[144:147], v[168:171], v[56:59]
	v_mfma_f32_16x16x32_bf16 v[48:51], v[160:163], v[168:171], v[48:51]
	v_mfma_f32_16x16x32_bf16 v[40:43], v[144:147], v[176:179], v[40:43]
	v_mfma_f32_16x16x32_bf16 v[32:35], v[160:163], v[176:179], v[32:35]
	v_mfma_f32_16x16x32_bf16 v[24:27], v[144:147], v[184:187], v[24:27]
	v_mfma_f32_16x16x32_bf16 v[16:19], v[160:163], v[184:187], v[16:19]
	v_mfma_f32_16x16x32_bf16 v[8:11], v[144:147], v[192:195], v[8:11]
	v_mfma_f32_16x16x32_bf16 v[4:7], v[160:163], v[192:195], v[4:7]
	v_mfma_f32_16x16x32_bf16 v[56:59], v[156:159], v[172:175], v[56:59]
	v_mfma_f32_16x16x32_bf16 v[48:51], v[164:167], v[172:175], v[48:51]
	v_mfma_f32_16x16x32_bf16 v[40:43], v[156:159], v[180:183], v[40:43]
	v_mfma_f32_16x16x32_bf16 v[32:35], v[164:167], v[180:183], v[32:35]
	v_mfma_f32_16x16x32_bf16 v[24:27], v[156:159], v[188:191], v[24:27]
	v_mfma_f32_16x16x32_bf16 v[16:19], v[164:167], v[188:191], v[16:19]
	v_mfma_f32_16x16x32_bf16 v[8:11], v[156:159], v[196:199], v[8:11]
	v_mfma_f32_16x16x32_bf16 v[4:7], v[164:167], v[196:199], v[4:7]
	s_setprio 0
	s_barrier
; #define PG8_STAGE(bufoff, gbase, voff) do { _Pragma("unroll") for (int _i = 0; _i < 2; ++_i) \
;         __builtin_amdgcn_global_load_lds((const unsigned*)((const char*)(gbase) + (voff)[_i]), (LAS unsigned*)(lds + (bufoff) + ldsw + _i * 8192), 16, 0, 0); } while (0)
; #define PG8_LDA(dst, b, h) do { _Pragma("unroll") for (int m = 0; m < 4; ++m) _Pragma("unroll") for (int k = 0; k < 2; ++k) dst[m][k] = *(const LAS bf16x8*)(lds + PG8_SA(b, h) + aoff + m * 2048 + k * 1024); } while (0)
; #define PG8_LDB(dst, b, h) do { _Pragma("unroll") for (int n = 0; n < 2; ++n) _Pragma("unroll") for (int k = 0; k < 2; ++k) dst[n][k] = *(const LAS bf16x8*)(lds + PG8_SB(b, h) + boff + n * 2048 + k * 1024); } while (0)
; #define PG8_MMA(ai, bj, At, Bt) do { __builtin_amdgcn_s_setprio(1); _Pragma("unroll") for (int m = 0; m < 4; ++m) _Pragma("unroll") for (int n = 0; n < 2; ++n) _Pragma("unroll") for (int k = 0; k < 2; ++k) \
;         acc[ai][bj][m][n] = __builtin_amdgcn_mfma_f32_16x16x32_bf16(Bt[n][k], At[m][k], acc[ai][bj][m][n], 0, 0, 0); __builtin_amdgcn_s_setprio(0); } while (0)
; #define PG8_WAIT_V(n) asm volatile("s_waitcnt vmcnt(" #n ")" ::: "memory")
; #define PG8_WAIT_L(n) asm volatile("s_waitcnt lgkmcnt(" #n ")" ::: "memory")
; #define PG8_BAR __builtin_amdgcn_s_barrier()
; #define PG8_SCHED __builtin_amdgcn_sched_barrier(0)
; template <class Epi>
; __device__ __forceinline__ void gemm_phase(LAS unsigned char* lds, const Gemm g, const StaticOrder& S, const Epi& E) {
;     ...
;             PG8_STAGE(PG8_SB(0, 1), b2 + hstepB, voffB);
;             PG8_WAIT_V(6); PG8_BAR; PG8_MMA(1, 1, At, B1); PG8_BAR;
;             PG8_LDB(B0, 1, 0); PG8_SCHED; PG8_LDA(At, 1, 0); PG8_STAGE(PG8_SA(0, 1), a2 + hstepA, voffA);
;             PG8_WAIT_L(8); PG8_BAR; PG8_WAIT_L(0); PG8_MMA(0, 0, At, B0); PG8_BAR; PG8_SCHED;
;             PG8_LDB(B1, 1, 1); PG8_STAGE(PG8_SB(1, 0), b3, voffB);
	s_add_u32 s66, s26, 0x40000
	s_addc_u32 s67, s27, 0
	s_add_i32 s78, s60, s36
	v_lshl_add_u64 v[144:145], s[66:67], 0, v[130:131]
	s_mov_b32 m0, s78
	s_nop 0
	global_load_lds_dwordx4 v[144:145], off
	v_lshl_add_u64 v[144:145], s[66:67], 0, v[134:135]
	s_add_i32 m0, s78, 0x2000
	s_nop 0
	global_load_lds_dwordx4 v[144:145], off
	s_waitcnt vmcnt(6)
	s_barrier
	s_setprio 1
	v_mfma_f32_16x16x32_bf16 v[60:63], v[200:203], v[168:171], v[60:63]
	v_mfma_f32_16x16x32_bf16 v[52:55], v[212:215], v[168:171], v[52:55]
	v_mfma_f32_16x16x32_bf16 v[44:47], v[200:203], v[176:179], v[44:47]
	v_mfma_f32_16x16x32_bf16 v[36:39], v[212:215], v[176:179], v[36:39]
	v_mfma_f32_16x16x32_bf16 v[28:31], v[200:203], v[184:187], v[28:31]
	v_mfma_f32_16x16x32_bf16 v[20:23], v[212:215], v[184:187], v[20:23]
	v_mfma_f32_16x16x32_bf16 v[12:15], v[200:203], v[192:195], v[12:15]
	v_mfma_f32_16x16x32_bf16 v[0:3], v[212:215], v[192:195], v[0:3]
	v_mfma_f32_16x16x32_bf16 v[60:63], v[204:207], v[172:175], v[60:63]
	v_mfma_f32_16x16x32_bf16 v[52:55], v[216:219], v[172:175], v[52:55]
	v_mfma_f32_16x16x32_bf16 v[44:47], v[204:207], v[180:183], v[44:47]
	v_mfma_f32_16x16x32_bf16 v[36:39], v[216:219], v[180:183], v[36:39]
	v_mfma_f32_16x16x32_bf16 v[28:31], v[204:207], v[188:191], v[28:31]
	v_mfma_f32_16x16x32_bf16 v[20:23], v[216:219], v[188:191], v[20:23]
	v_mfma_f32_16x16x32_bf16 v[12:15], v[204:207], v[196:199], v[12:15]
	v_mfma_f32_16x16x32_bf16 v[0:3], v[216:219], v[196:199], v[0:3]
	s_setprio 0
	s_add_i32 s66, 0, 0x18000
	v_add_u32_e32 v155, s66, v150
	s_barrier
	ds_read_b128 v[144:147], v155
	ds_read_b128 v[156:159], v155 offset:1024
	ds_read_b128 v[160:163], v155 offset:2048
	ds_read_b128 v[164:167], v155 offset:3072
	s_add_u32 s28, s28, 0x40000
	s_addc_u32 s29, s29, 0
	s_mov_b32 m0, s39
	v_lshl_add_u64 v[200:201], s[28:29], 0, v[128:129]
	ds_read_b128 v[168:171], v152 offset:32768
	ds_read_b128 v[172:175], v152 offset:33792
	ds_read_b128 v[176:179], v152 offset:34816
	ds_read_b128 v[180:183], v152 offset:35840
	ds_read_b128 v[184:187], v152 offset:36864
	ds_read_b128 v[188:191], v152 offset:37888
	ds_read_b128 v[192:195], v152 offset:38912
	ds_read_b128 v[196:199], v152 offset:39936
	global_load_lds_dwordx4 v[200:201], off
	v_lshl_add_u64 v[200:201], s[28:29], 0, v[132:133]
	s_mov_b32 m0, s40
	s_nop 0
	global_load_lds_dwordx4 v[200:201], off
	s_waitcnt lgkmcnt(8)
	s_barrier
	s_waitcnt lgkmcnt(0)
	s_setprio 1
	s_waitcnt lgkmcnt(0)
	v_mfma_f32_16x16x32_bf16 v[116:119], v[144:147], v[168:171], v[116:119]
	v_mfma_f32_16x16x32_bf16 v[112:115], v[160:163], v[168:171], v[112:115]
	v_mfma_f32_16x16x32_bf16 v[104:107], v[144:147], v[176:179], v[104:107]
	v_mfma_f32_16x16x32_bf16 v[96:99], v[160:163], v[176:179], v[96:99]
	v_mfma_f32_16x16x32_bf16 v[88:91], v[144:147], v[184:187], v[88:91]
	v_mfma_f32_16x16x32_bf16 v[80:83], v[160:163], v[184:187], v[80:83]
	v_mfma_f32_16x16x32_bf16 v[72:75], v[144:147], v[192:195], v[72:75]
	v_mfma_f32_16x16x32_bf16 v[64:67], v[160:163], v[192:195], v[64:67]
	v_mfma_f32_16x16x32_bf16 v[116:119], v[156:159], v[172:175], v[116:119]
	v_mfma_f32_16x16x32_bf16 v[112:115], v[164:167], v[172:175], v[112:115]
	v_mfma_f32_16x16x32_bf16 v[104:107], v[156:159], v[180:183], v[104:107]
	v_mfma_f32_16x16x32_bf16 v[96:99], v[164:167], v[180:183], v[96:99]
	v_mfma_f32_16x16x32_bf16 v[88:91], v[156:159], v[188:191], v[88:91]
	v_mfma_f32_16x16x32_bf16 v[80:83], v[164:167], v[188:191], v[80:83]
	v_mfma_f32_16x16x32_bf16 v[72:75], v[156:159], v[196:199], v[72:75]
	v_mfma_f32_16x16x32_bf16 v[64:67], v[164:167], v[196:199], v[64:67]
	s_setprio 0
	s_barrier
	s_add_i32 s28, 0, 0x1c000
	s_add_i32 s29, s66, s36
	v_add_u32_e32 v155, s28, v150
	v_lshl_add_u64 v[208:209], v[208:209], 0, s[12:13]
	s_mov_b32 m0, s29
	ds_read_b128 v[200:203], v155
	ds_read_b128 v[204:207], v155 offset:1024
	ds_read_b128 v[212:215], v155 offset:2048
	ds_read_b128 v[216:219], v155 offset:3072
	global_load_lds_dwordx4 v[208:209], off
	v_lshl_add_u64 v[208:209], v[220:221], 0, s[12:13]
	s_add_i32 m0, s29, 0x2000
	s_nop 0
	global_load_lds_dwordx4 v[208:209], off
	s_barrier
; #define PG8_STAGE(bufoff, gbase, voff) do { _Pragma("unroll") for (int _i = 0; _i < 2; ++_i) \
;         __builtin_amdgcn_global_load_lds((const unsigned*)((const char*)(gbase) + (voff)[_i]), (LAS unsigned*)(lds + (bufoff) + ldsw + _i * 8192), 16, 0, 0); } while (0)
; #define PG8_LDA(dst, b, h) do { _Pragma("unroll") for (int m = 0; m < 4; ++m) _Pragma("unroll") for (int k = 0; k < 2; ++k) dst[m][k] = *(const LAS bf16x8*)(lds + PG8_SA(b, h) + aoff + m * 2048 + k * 1024); } while (0)
; #define PG8_LDB(dst, b, h) do { _Pragma("unroll") for (int n = 0; n < 2; ++n) _Pragma("unroll") for (int k = 0; k < 2; ++k) dst[n][k] = *(const LAS bf16x8*)(lds + PG8_SB(b, h) + boff + n * 2048 + k * 1024); } while (0)
; #define PG8_MMA(ai, bj, At, Bt) do { __builtin_amdgcn_s_setprio(1); _Pragma("unroll") for (int m = 0; m < 4; ++m) _Pragma("unroll") for (int n = 0; n < 2; ++n) _Pragma("unroll") for (int k = 0; k < 2; ++k) \
;         acc[ai][bj][m][n] = __builtin_amdgcn_mfma_f32_16x16x32_bf16(Bt[n][k], At[m][k], acc[ai][bj][m][n], 0, 0, 0); __builtin_amdgcn_s_setprio(0); } while (0)
; #define PG8_WAIT_V(n) asm volatile("s_waitcnt vmcnt(" #n ")" ::: "memory")
; #define PG8_WAIT_L(n) asm volatile("s_waitcnt lgkmcnt(" #n ")" ::: "memory")
; #define PG8_BAR __builtin_amdgcn_s_barrier()
; #define PG8_SCHED __builtin_amdgcn_sched_barrier(0)
; template <class Epi>
; __device__ __forceinline__ void gemm_phase(LAS unsigned char* lds, const Gemm g, const StaticOrder& S, const Epi& E) {
;     ...
;             PG8_LDB(B1, 1, 1); PG8_STAGE(PG8_SB(1, 0), b3, voffB);
;             PG8_BAR; PG8_WAIT_L(0); PG8_MMA(0, 1, At, B1); PG8_BAR;
;             PG8_LDA(At, 1, 1); PG8_STAGE(PG8_SA(1, 0), a3, voffA);
;             PG8_BAR; PG8_WAIT_L(0); PG8_MMA(1, 0, At, B0); PG8_BAR; PG8_SCHED;
;             PG8_STAGE(PG8_SB(1, 1), b3 + hstepB, voffB);
;             PG8_WAIT_V(6); PG8_BAR; PG8_MMA(1, 1, At, B1); PG8_BAR;
	s_waitcnt lgkmcnt(0)
	s_setprio 1
	s_waitcnt lgkmcnt(0)
	v_mfma_f32_16x16x32_bf16 v[124:127], v[200:203], v[168:171], v[124:127]
	v_mfma_f32_16x16x32_bf16 v[120:123], v[212:215], v[168:171], v[120:123]
	v_mfma_f32_16x16x32_bf16 v[108:111], v[200:203], v[176:179], v[108:111]
	v_mfma_f32_16x16x32_bf16 v[100:103], v[212:215], v[176:179], v[100:103]
	v_mfma_f32_16x16x32_bf16 v[92:95], v[200:203], v[184:187], v[92:95]
	v_mfma_f32_16x16x32_bf16 v[84:87], v[212:215], v[184:187], v[84:87]
	v_mfma_f32_16x16x32_bf16 v[76:79], v[200:203], v[192:195], v[76:79]
	v_mfma_f32_16x16x32_bf16 v[68:71], v[212:215], v[192:195], v[68:71]
	v_mfma_f32_16x16x32_bf16 v[124:127], v[204:207], v[172:175], v[124:127]
	v_mfma_f32_16x16x32_bf16 v[120:123], v[216:219], v[172:175], v[120:123]
	v_mfma_f32_16x16x32_bf16 v[108:111], v[204:207], v[180:183], v[108:111]
	v_mfma_f32_16x16x32_bf16 v[100:103], v[216:219], v[180:183], v[100:103]
	v_mfma_f32_16x16x32_bf16 v[92:95], v[204:207], v[188:191], v[92:95]
	v_mfma_f32_16x16x32_bf16 v[84:87], v[216:219], v[188:191], v[84:87]
	v_mfma_f32_16x16x32_bf16 v[76:79], v[204:207], v[196:199], v[76:79]
	v_mfma_f32_16x16x32_bf16 v[68:71], v[216:219], v[196:199], v[68:71]
	s_setprio 0
	s_mov_b32 m0, s44
	v_lshl_add_u64 v[208:209], v[222:223], 0, s[12:13]
	s_barrier
	ds_read_b128 v[168:171], v152 offset:49152
	ds_read_b128 v[172:175], v152 offset:50176
	ds_read_b128 v[176:179], v152 offset:51200
	ds_read_b128 v[180:183], v152 offset:52224
	ds_read_b128 v[184:187], v152 offset:53248
	ds_read_b128 v[188:191], v152 offset:54272
	ds_read_b128 v[192:195], v152 offset:55296
	ds_read_b128 v[196:199], v152 offset:56320
	global_load_lds_dwordx4 v[208:209], off
	v_lshl_add_u64 v[208:209], v[224:225], 0, s[12:13]
	s_mov_b32 m0, s45
	s_nop 0
	global_load_lds_dwordx4 v[208:209], off
	s_barrier
	s_waitcnt lgkmcnt(0)
	s_setprio 1
	s_waitcnt lgkmcnt(0)
	v_mfma_f32_16x16x32_bf16 v[56:59], v[144:147], v[168:171], v[56:59]
	v_mfma_f32_16x16x32_bf16 v[48:51], v[160:163], v[168:171], v[48:51]
	v_mfma_f32_16x16x32_bf16 v[40:43], v[144:147], v[176:179], v[40:43]
	v_mfma_f32_16x16x32_bf16 v[32:35], v[160:163], v[176:179], v[32:35]
	v_mfma_f32_16x16x32_bf16 v[24:27], v[144:147], v[184:187], v[24:27]
	v_mfma_f32_16x16x32_bf16 v[16:19], v[160:163], v[184:187], v[16:19]
	v_mfma_f32_16x16x32_bf16 v[8:11], v[144:147], v[192:195], v[8:11]
	v_mfma_f32_16x16x32_bf16 v[4:7], v[160:163], v[192:195], v[4:7]
	v_mfma_f32_16x16x32_bf16 v[56:59], v[156:159], v[172:175], v[56:59]
	v_mfma_f32_16x16x32_bf16 v[48:51], v[164:167], v[172:175], v[48:51]
	v_mfma_f32_16x16x32_bf16 v[40:43], v[156:159], v[180:183], v[40:43]
	v_mfma_f32_16x16x32_bf16 v[32:35], v[164:167], v[180:183], v[32:35]
	v_mfma_f32_16x16x32_bf16 v[24:27], v[156:159], v[188:191], v[24:27]
	v_mfma_f32_16x16x32_bf16 v[16:19], v[164:167], v[188:191], v[16:19]
	v_mfma_f32_16x16x32_bf16 v[8:11], v[156:159], v[196:199], v[8:11]
	v_mfma_f32_16x16x32_bf16 v[4:7], v[164:167], v[196:199], v[4:7]
	s_setprio 0
	s_barrier
	s_add_u32 s26, s26, 0x40080
	s_addc_u32 s27, s27, 0
	s_add_i32 s28, s28, s36
	v_lshl_add_u64 v[144:145], s[26:27], 0, v[130:131]
	s_mov_b32 m0, s28
	s_nop 0
	global_load_lds_dwordx4 v[144:145], off
	v_lshl_add_u64 v[144:145], s[26:27], 0, v[134:135]
	s_add_i32 m0, s28, 0x2000
	s_nop 0
	global_load_lds_dwordx4 v[144:145], off
	s_waitcnt vmcnt(6)
	s_barrier
	s_setprio 1
	v_mfma_f32_16x16x32_bf16 v[60:63], v[200:203], v[168:171], v[60:63]
	v_mfma_f32_16x16x32_bf16 v[52:55], v[212:215], v[168:171], v[52:55]
	v_mfma_f32_16x16x32_bf16 v[44:47], v[200:203], v[176:179], v[44:47]
	v_mfma_f32_16x16x32_bf16 v[36:39], v[212:215], v[176:179], v[36:39]
	v_mfma_f32_16x16x32_bf16 v[28:31], v[200:203], v[184:187], v[28:31]
	v_mfma_f32_16x16x32_bf16 v[20:23], v[212:215], v[184:187], v[20:23]
	v_mfma_f32_16x16x32_bf16 v[12:15], v[200:203], v[192:195], v[12:15]
	v_mfma_f32_16x16x32_bf16 v[0:3], v[212:215], v[192:195], v[0:3]
	v_mfma_f32_16x16x32_bf16 v[60:63], v[204:207], v[172:175], v[60:63]
	v_mfma_f32_16x16x32_bf16 v[52:55], v[216:219], v[172:175], v[52:55]
	v_mfma_f32_16x16x32_bf16 v[44:47], v[204:207], v[180:183], v[44:47]
	v_mfma_f32_16x16x32_bf16 v[36:39], v[216:219], v[180:183], v[36:39]
	v_mfma_f32_16x16x32_bf16 v[28:31], v[204:207], v[188:191], v[28:31]
	v_mfma_f32_16x16x32_bf16 v[20:23], v[216:219], v[188:191], v[20:23]
	v_mfma_f32_16x16x32_bf16 v[12:15], v[204:207], v[196:199], v[12:15]
	v_mfma_f32_16x16x32_bf16 v[0:3], v[216:219], v[196:199], v[0:3]
	s_setprio 0
	s_add_u32 s8, s8, 0x100
	s_addc_u32 s9, s9, 0
	s_add_u32 s65, s65, 0x100
	s_addc_u32 s76, s76, 0
	s_cmp_ge_i32 s77, s43
	s_mov_b32 s26, s77
	s_barrier
	s_cbranch_scc0 .LBB0_2411
	s_branch .LBB0_2402

; __global__ void __launch_bounds__(NT, 2) fwd_kernel(Params P) {
	.amdhsa_kernel _Z10fwd_kernel6Params
		.amdhsa_group_segment_fixed_size 0
		.amdhsa_private_segment_fixed_size 0
		.amdhsa_kernarg_size 464
		.amdhsa_user_sgpr_count 2
		.amdhsa_user_sgpr_dispatch_ptr 0
		.amdhsa_user_sgpr_queue_ptr 0
		.amdhsa_user_sgpr_kernarg_segment_ptr 1
		.amdhsa_user_sgpr_dispatch_id 0
		.amdhsa_user_sgpr_kernarg_preload_length 0
		.amdhsa_user_sgpr_kernarg_preload_offset 0
		.amdhsa_user_sgpr_private_segment_size 0
		.amdhsa_uses_dynamic_stack 0
		.amdhsa_enable_private_segment 0
		.amdhsa_system_sgpr_workgroup_id_x 1
		.amdhsa_system_sgpr_workgroup_id_y 0
		.amdhsa_system_sgpr_workgroup_id_z 0
		.amdhsa_system_sgpr_workgroup_info 0
		.amdhsa_system_vgpr_workitem_id 2
		.amdhsa_next_free_vgpr 256
		.amdhsa_next_free_sgpr 102
		.amdhsa_accum_offset 256
		.amdhsa_reserve_vcc 1
		.amdhsa_float_round_mode_32 0
		.amdhsa_float_round_mode_16_64 0
		.amdhsa_float_denorm_mode_32 3
		.amdhsa_float_denorm_mode_16_64 3
		.amdhsa_dx10_clamp 1
		.amdhsa_ieee_mode 1
		.amdhsa_fp16_overflow 0
		.amdhsa_tg_split 0
		.amdhsa_exception_fp_ieee_invalid_op 0
		.amdhsa_exception_fp_denorm_src 0
		.amdhsa_exception_fp_ieee_div_zero 0
		.amdhsa_exception_fp_ieee_overflow 0
		.amdhsa_exception_fp_ieee_underflow 0
		.amdhsa_exception_fp_ieee_inexact 0
		.amdhsa_exception_int_div_zero 0
	.end_amdhsa_kernel

; __global__ void __launch_bounds__(NT, 2) fwd_kernel(Params P) {
amdhsa.kernels:
  - .agpr_count:     0
    .args:
      - .offset:         0
        .size:           208
        .value_kind:     by_value
      - .offset:         208
        .size:           4
        .value_kind:     hidden_block_count_x
      - .offset:         212
        .size:           4
        .value_kind:     hidden_block_count_y
      - .offset:         216
        .size:           4
        .value_kind:     hidden_block_count_z
      - .offset:         220
        .size:           2
        .value_kind:     hidden_group_size_x
      - .offset:         222
        .size:           2
        .value_kind:     hidden_group_size_y
      - .offset:         224
        .size:           2
        .value_kind:     hidden_group_size_z
      - .offset:         226
        .size:           2
        .value_kind:     hidden_remainder_x
      - .offset:         228
        .size:           2
        .value_kind:     hidden_remainder_y
      - .offset:         230
        .size:           2
        .value_kind:     hidden_remainder_z
      - .offset:         248
        .size:           8
        .value_kind:     hidden_global_offset_x
      - .offset:         256
        .size:           8
        .value_kind:     hidden_global_offset_y
      - .offset:         264
        .size:           8
        .value_kind:     hidden_global_offset_z
      - .offset:         272
        .size:           2
        .value_kind:     hidden_grid_dims
      - .offset:         296
        .size:           8
        .value_kind:     hidden_multigrid_sync_arg
      - .offset:         328
        .size:           4
        .value_kind:     hidden_dynamic_lds_size
    .group_segment_fixed_size: 0
    .kernarg_segment_align: 8
    .kernarg_segment_size: 464
    .language:       OpenCL C
    .language_version:
      - 2
      - 0
    .max_flat_workgroup_size: 512
    .name:           _Z10fwd_kernel6Params
    .private_segment_fixed_size: 0
    .sgpr_count:     108
    .sgpr_spill_count: 6
    .symbol:         _Z10fwd_kernel6Params.kd
    .uniform_work_group_size: 1
    .uses_dynamic_stack: false
    .vgpr_count:     256
    .vgpr_spill_count: 0
    .wavefront_size: 64
